# mod_item mat-vec: 64 weight loads in flight (straight-line, same FMA order) instead of 4-load vmcnt(0) trips
# speedup vs baseline: 1.0100x; 1.0100x over previous
.LBB0_1823:
	s_waitcnt vmcnt(0)
	v_mov_b32_e32 v144, v4
	v_mov_b32_e32 v145, v5
	global_load_dword v80, v[144:145], off
	v_add_co_u32_e32 v144, vcc, s33, v144
	s_nop 1
	v_addc_co_u32_e32 v145, vcc, 0, v145, vcc
	global_load_dword v81, v[144:145], off
	v_add_co_u32_e32 v144, vcc, s33, v144
	s_nop 1
	v_addc_co_u32_e32 v145, vcc, 0, v145, vcc
	global_load_dword v82, v[144:145], off
	v_add_co_u32_e32 v144, vcc, s33, v144
	s_nop 1
	v_addc_co_u32_e32 v145, vcc, 0, v145, vcc
	global_load_dword v83, v[144:145], off
	v_add_co_u32_e32 v144, vcc, s33, v144
	s_nop 1
	v_addc_co_u32_e32 v145, vcc, 0, v145, vcc
	global_load_dword v84, v[144:145], off
	v_add_co_u32_e32 v144, vcc, s33, v144
	s_nop 1
	v_addc_co_u32_e32 v145, vcc, 0, v145, vcc
	global_load_dword v85, v[144:145], off
	v_add_co_u32_e32 v144, vcc, s33, v144
	s_nop 1
	v_addc_co_u32_e32 v145, vcc, 0, v145, vcc
	global_load_dword v86, v[144:145], off
	v_add_co_u32_e32 v144, vcc, s33, v144
	s_nop 1
	v_addc_co_u32_e32 v145, vcc, 0, v145, vcc
	global_load_dword v87, v[144:145], off
	v_add_co_u32_e32 v144, vcc, s33, v144
	s_nop 1
	v_addc_co_u32_e32 v145, vcc, 0, v145, vcc
	global_load_dword v88, v[144:145], off
	v_add_co_u32_e32 v144, vcc, s33, v144
	s_nop 1
	v_addc_co_u32_e32 v145, vcc, 0, v145, vcc
	global_load_dword v89, v[144:145], off
	v_add_co_u32_e32 v144, vcc, s33, v144
	s_nop 1
	v_addc_co_u32_e32 v145, vcc, 0, v145, vcc
	global_load_dword v90, v[144:145], off
	v_add_co_u32_e32 v144, vcc, s33, v144
	s_nop 1
	v_addc_co_u32_e32 v145, vcc, 0, v145, vcc
	global_load_dword v91, v[144:145], off
	v_add_co_u32_e32 v144, vcc, s33, v144
	s_nop 1
	v_addc_co_u32_e32 v145, vcc, 0, v145, vcc
	global_load_dword v92, v[144:145], off
	v_add_co_u32_e32 v144, vcc, s33, v144
	s_nop 1
	v_addc_co_u32_e32 v145, vcc, 0, v145, vcc
	global_load_dword v93, v[144:145], off
	v_add_co_u32_e32 v144, vcc, s33, v144
	s_nop 1
	v_addc_co_u32_e32 v145, vcc, 0, v145, vcc
	global_load_dword v94, v[144:145], off
	v_add_co_u32_e32 v144, vcc, s33, v144
	s_nop 1
	v_addc_co_u32_e32 v145, vcc, 0, v145, vcc
	global_load_dword v95, v[144:145], off
	v_add_co_u32_e32 v144, vcc, s33, v144
	s_nop 1
	v_addc_co_u32_e32 v145, vcc, 0, v145, vcc
	global_load_dword v96, v[144:145], off
	v_add_co_u32_e32 v144, vcc, s33, v144
	s_nop 1
	v_addc_co_u32_e32 v145, vcc, 0, v145, vcc
	global_load_dword v97, v[144:145], off
	v_add_co_u32_e32 v144, vcc, s33, v144
	s_nop 1
	v_addc_co_u32_e32 v145, vcc, 0, v145, vcc
	global_load_dword v98, v[144:145], off
	v_add_co_u32_e32 v144, vcc, s33, v144
	s_nop 1
	v_addc_co_u32_e32 v145, vcc, 0, v145, vcc
	global_load_dword v99, v[144:145], off
	v_add_co_u32_e32 v144, vcc, s33, v144
	s_nop 1
	v_addc_co_u32_e32 v145, vcc, 0, v145, vcc
	global_load_dword v100, v[144:145], off
	v_add_co_u32_e32 v144, vcc, s33, v144
	s_nop 1
	v_addc_co_u32_e32 v145, vcc, 0, v145, vcc
	global_load_dword v101, v[144:145], off
	v_add_co_u32_e32 v144, vcc, s33, v144
	s_nop 1
	v_addc_co_u32_e32 v145, vcc, 0, v145, vcc
	global_load_dword v102, v[144:145], off
	v_add_co_u32_e32 v144, vcc, s33, v144
	s_nop 1
	v_addc_co_u32_e32 v145, vcc, 0, v145, vcc
	global_load_dword v103, v[144:145], off
	v_add_co_u32_e32 v144, vcc, s33, v144
	s_nop 1
	v_addc_co_u32_e32 v145, vcc, 0, v145, vcc
	global_load_dword v104, v[144:145], off
	v_add_co_u32_e32 v144, vcc, s33, v144
	s_nop 1
	v_addc_co_u32_e32 v145, vcc, 0, v145, vcc
	global_load_dword v105, v[144:145], off
	v_add_co_u32_e32 v144, vcc, s33, v144
	s_nop 1
	v_addc_co_u32_e32 v145, vcc, 0, v145, vcc
	global_load_dword v106, v[144:145], off
	v_add_co_u32_e32 v144, vcc, s33, v144
	s_nop 1
	v_addc_co_u32_e32 v145, vcc, 0, v145, vcc
	global_load_dword v107, v[144:145], off
	v_add_co_u32_e32 v144, vcc, s33, v144
	s_nop 1
	v_addc_co_u32_e32 v145, vcc, 0, v145, vcc
	global_load_dword v108, v[144:145], off
	v_add_co_u32_e32 v144, vcc, s33, v144
	s_nop 1
	v_addc_co_u32_e32 v145, vcc, 0, v145, vcc
	global_load_dword v109, v[144:145], off
	v_add_co_u32_e32 v144, vcc, s33, v144
	s_nop 1
	v_addc_co_u32_e32 v145, vcc, 0, v145, vcc
	global_load_dword v110, v[144:145], off
	v_add_co_u32_e32 v144, vcc, s33, v144
	s_nop 1
	v_addc_co_u32_e32 v145, vcc, 0, v145, vcc
	global_load_dword v111, v[144:145], off
	v_add_co_u32_e32 v144, vcc, s33, v144
	s_nop 1
	v_addc_co_u32_e32 v145, vcc, 0, v145, vcc
	global_load_dword v112, v[144:145], off
	v_add_co_u32_e32 v144, vcc, s33, v144
	s_nop 1
	v_addc_co_u32_e32 v145, vcc, 0, v145, vcc
	global_load_dword v113, v[144:145], off
	v_add_co_u32_e32 v144, vcc, s33, v144
	s_nop 1
	v_addc_co_u32_e32 v145, vcc, 0, v145, vcc
	global_load_dword v114, v[144:145], off
	v_add_co_u32_e32 v144, vcc, s33, v144
	s_nop 1
	v_addc_co_u32_e32 v145, vcc, 0, v145, vcc
	global_load_dword v115, v[144:145], off
	v_add_co_u32_e32 v144, vcc, s33, v144
	s_nop 1
	v_addc_co_u32_e32 v145, vcc, 0, v145, vcc
	global_load_dword v116, v[144:145], off
	v_add_co_u32_e32 v144, vcc, s33, v144
	s_nop 1
	v_addc_co_u32_e32 v145, vcc, 0, v145, vcc
	global_load_dword v117, v[144:145], off
	v_add_co_u32_e32 v144, vcc, s33, v144
	s_nop 1
	v_addc_co_u32_e32 v145, vcc, 0, v145, vcc
	global_load_dword v118, v[144:145], off
	v_add_co_u32_e32 v144, vcc, s33, v144
	s_nop 1
	v_addc_co_u32_e32 v145, vcc, 0, v145, vcc
	global_load_dword v119, v[144:145], off
	v_add_co_u32_e32 v144, vcc, s33, v144
	s_nop 1
	v_addc_co_u32_e32 v145, vcc, 0, v145, vcc
	global_load_dword v120, v[144:145], off
	v_add_co_u32_e32 v144, vcc, s33, v144
	s_nop 1
	v_addc_co_u32_e32 v145, vcc, 0, v145, vcc
	global_load_dword v121, v[144:145], off
	v_add_co_u32_e32 v144, vcc, s33, v144
	s_nop 1
	v_addc_co_u32_e32 v145, vcc, 0, v145, vcc
	global_load_dword v122, v[144:145], off
	v_add_co_u32_e32 v144, vcc, s33, v144
	s_nop 1
	v_addc_co_u32_e32 v145, vcc, 0, v145, vcc
	global_load_dword v123, v[144:145], off
	v_add_co_u32_e32 v144, vcc, s33, v144
	s_nop 1
	v_addc_co_u32_e32 v145, vcc, 0, v145, vcc
	global_load_dword v124, v[144:145], off
	v_add_co_u32_e32 v144, vcc, s33, v144
	s_nop 1
	v_addc_co_u32_e32 v145, vcc, 0, v145, vcc
	global_load_dword v125, v[144:145], off
	v_add_co_u32_e32 v144, vcc, s33, v144
	s_nop 1
	v_addc_co_u32_e32 v145, vcc, 0, v145, vcc
	global_load_dword v126, v[144:145], off
	v_add_co_u32_e32 v144, vcc, s33, v144
	s_nop 1
	v_addc_co_u32_e32 v145, vcc, 0, v145, vcc
	global_load_dword v127, v[144:145], off
	v_add_co_u32_e32 v144, vcc, s33, v144
	s_nop 1
	v_addc_co_u32_e32 v145, vcc, 0, v145, vcc
	global_load_dword v128, v[144:145], off
	v_add_co_u32_e32 v144, vcc, s33, v144
	s_nop 1
	v_addc_co_u32_e32 v145, vcc, 0, v145, vcc
	global_load_dword v129, v[144:145], off
	v_add_co_u32_e32 v144, vcc, s33, v144
	s_nop 1
	v_addc_co_u32_e32 v145, vcc, 0, v145, vcc
	global_load_dword v130, v[144:145], off
	v_add_co_u32_e32 v144, vcc, s33, v144
	s_nop 1
	v_addc_co_u32_e32 v145, vcc, 0, v145, vcc
	global_load_dword v131, v[144:145], off
	v_add_co_u32_e32 v144, vcc, s33, v144
	s_nop 1
	v_addc_co_u32_e32 v145, vcc, 0, v145, vcc
	global_load_dword v132, v[144:145], off
	v_add_co_u32_e32 v144, vcc, s33, v144
	s_nop 1
	v_addc_co_u32_e32 v145, vcc, 0, v145, vcc
	global_load_dword v133, v[144:145], off
	v_add_co_u32_e32 v144, vcc, s33, v144
	s_nop 1
	v_addc_co_u32_e32 v145, vcc, 0, v145, vcc
	global_load_dword v134, v[144:145], off
	v_add_co_u32_e32 v144, vcc, s33, v144
	s_nop 1
	v_addc_co_u32_e32 v145, vcc, 0, v145, vcc
	global_load_dword v135, v[144:145], off
	v_add_co_u32_e32 v144, vcc, s33, v144
	s_nop 1
	v_addc_co_u32_e32 v145, vcc, 0, v145, vcc
	global_load_dword v136, v[144:145], off
	v_add_co_u32_e32 v144, vcc, s33, v144
	s_nop 1
	v_addc_co_u32_e32 v145, vcc, 0, v145, vcc
	global_load_dword v137, v[144:145], off
	v_add_co_u32_e32 v144, vcc, s33, v144
	s_nop 1
	v_addc_co_u32_e32 v145, vcc, 0, v145, vcc
	global_load_dword v138, v[144:145], off
	v_add_co_u32_e32 v144, vcc, s33, v144
	s_nop 1
	v_addc_co_u32_e32 v145, vcc, 0, v145, vcc
	global_load_dword v139, v[144:145], off
	v_add_co_u32_e32 v144, vcc, s33, v144
	s_nop 1
	v_addc_co_u32_e32 v145, vcc, 0, v145, vcc
	global_load_dword v140, v[144:145], off
	v_add_co_u32_e32 v144, vcc, s33, v144
	s_nop 1
	v_addc_co_u32_e32 v145, vcc, 0, v145, vcc
	global_load_dword v141, v[144:145], off
	v_add_co_u32_e32 v144, vcc, s33, v144
	s_nop 1
	v_addc_co_u32_e32 v145, vcc, 0, v145, vcc
	global_load_dword v142, v[144:145], off
	v_add_co_u32_e32 v144, vcc, s33, v144
	s_nop 1
	v_addc_co_u32_e32 v145, vcc, 0, v145, vcc
	global_load_dword v143, v[144:145], off
	v_add_co_u32_e32 v144, vcc, s33, v144
	s_nop 1
	v_addc_co_u32_e32 v145, vcc, 0, v145, vcc
	s_waitcnt vmcnt(60)
	v_mov_b32_e32 v52, v80
	v_mov_b32_e32 v54, v81
	v_mov_b32_e32 v56, v82
	v_mov_b32_e32 v58, v83
	global_load_dword v80, v[144:145], off
	v_add_co_u32_e32 v144, vcc, s33, v144
	s_nop 1
	v_addc_co_u32_e32 v145, vcc, 0, v145, vcc
	global_load_dword v81, v[144:145], off
	v_add_co_u32_e32 v144, vcc, s33, v144
	s_nop 1
	v_addc_co_u32_e32 v145, vcc, 0, v145, vcc
	global_load_dword v82, v[144:145], off
	v_add_co_u32_e32 v144, vcc, s33, v144
	s_nop 1
	v_addc_co_u32_e32 v145, vcc, 0, v145, vcc
	global_load_dword v83, v[144:145], off
	v_add_co_u32_e32 v144, vcc, s33, v144
	s_nop 1
	v_addc_co_u32_e32 v145, vcc, 0, v145, vcc
	ds_read_b128 v[16:19], v3 offset:4096
	ds_read_b128 v[20:23], v3 offset:8192
	ds_read_b128 v[24:27], v3 offset:12288
	ds_read_b128 v[28:31], v3 offset:16384
	ds_read_b128 v[32:35], v3 offset:20480
	ds_read_b128 v[36:39], v3 offset:24576
	ds_read_b128 v[40:43], v3 offset:28672
	ds_read_b128 v[44:47], v3
	ds_read_b128 v[48:51], v3 offset:32768
	s_waitcnt lgkmcnt(8)
	v_mov_b32_e32 v61, v16
	s_waitcnt lgkmcnt(7)
	v_mov_b32_e32 v62, v20
	s_waitcnt lgkmcnt(6)
	v_mov_b32_e32 v63, v24
	s_waitcnt lgkmcnt(1)
	v_mov_b32_e32 v60, v44
	v_mov_b32_e32 v64, v28
	v_mov_b32_e32 v65, v32
	v_mov_b32_e32 v66, v36
	v_mov_b32_e32 v67, v40
	v_mov_b32_e32 v16, v45
	v_mov_b32_e32 v24, v21
	v_mov_b32_e32 v32, v29
	v_mov_b32_e32 v40, v37
	v_mov_b32_e32 v20, v46
	v_mov_b32_e32 v21, v18
	v_mov_b32_e32 v28, v22
	v_mov_b32_e32 v29, v26
	v_mov_b32_e32 v36, v30
	v_mov_b32_e32 v37, v34
	v_mov_b32_e32 v44, v38
	v_mov_b32_e32 v45, v42
	v_mov_b32_e32 v18, v47
	v_mov_b32_e32 v26, v23
	v_mov_b32_e32 v34, v31
	v_mov_b32_e32 v42, v39
	v_add_u32_e32 v3, 16, v3
	v_pk_fma_f32 v[6:7], v[52:53], v[60:61], v[6:7] op_sel_hi:[0,1,1]
	v_pk_fma_f32 v[8:9], v[52:53], v[62:63], v[8:9] op_sel_hi:[0,1,1]
	v_pk_fma_f32 v[10:11], v[52:53], v[64:65], v[10:11] op_sel_hi:[0,1,1]
	v_pk_fma_f32 v[12:13], v[52:53], v[66:67], v[12:13] op_sel_hi:[0,1,1]
	s_waitcnt lgkmcnt(0)
	v_fmac_f32_e32 v15, v52, v48
	v_pk_fma_f32 v[6:7], v[54:55], v[16:17], v[6:7] op_sel_hi:[0,1,1]
	v_pk_fma_f32 v[8:9], v[54:55], v[24:25], v[8:9] op_sel_hi:[0,1,1]
	v_pk_fma_f32 v[10:11], v[54:55], v[32:33], v[10:11] op_sel_hi:[0,1,1]
	v_pk_fma_f32 v[12:13], v[54:55], v[40:41], v[12:13] op_sel_hi:[0,1,1]
	v_fmac_f32_e32 v15, v54, v49
	v_pk_fma_f32 v[6:7], v[56:57], v[20:21], v[6:7] op_sel_hi:[0,1,1]
	v_pk_fma_f32 v[8:9], v[56:57], v[28:29], v[8:9] op_sel_hi:[0,1,1]
	v_pk_fma_f32 v[10:11], v[56:57], v[36:37], v[10:11] op_sel_hi:[0,1,1]
	v_pk_fma_f32 v[12:13], v[56:57], v[44:45], v[12:13] op_sel_hi:[0,1,1]
	v_fmac_f32_e32 v15, v56, v50
	v_pk_fma_f32 v[6:7], v[58:59], v[18:19], v[6:7] op_sel_hi:[0,1,1]
	v_pk_fma_f32 v[8:9], v[58:59], v[26:27], v[8:9] op_sel_hi:[0,1,1]
	v_pk_fma_f32 v[10:11], v[58:59], v[34:35], v[10:11] op_sel_hi:[0,1,1]
	v_pk_fma_f32 v[12:13], v[58:59], v[42:43], v[12:13] op_sel_hi:[0,1,1]
	v_fmac_f32_e32 v15, v58, v51
	s_waitcnt vmcnt(60)
	v_mov_b32_e32 v52, v84
	v_mov_b32_e32 v54, v85
	v_mov_b32_e32 v56, v86
	v_mov_b32_e32 v58, v87
	global_load_dword v84, v[144:145], off
	v_add_co_u32_e32 v144, vcc, s33, v144
	s_nop 1
	v_addc_co_u32_e32 v145, vcc, 0, v145, vcc
	global_load_dword v85, v[144:145], off
	v_add_co_u32_e32 v144, vcc, s33, v144
	s_nop 1
	v_addc_co_u32_e32 v145, vcc, 0, v145, vcc
	global_load_dword v86, v[144:145], off
	v_add_co_u32_e32 v144, vcc, s33, v144
	s_nop 1
	v_addc_co_u32_e32 v145, vcc, 0, v145, vcc
	global_load_dword v87, v[144:145], off
	v_add_co_u32_e32 v144, vcc, s33, v144
	s_nop 1
	v_addc_co_u32_e32 v145, vcc, 0, v145, vcc
	ds_read_b128 v[16:19], v3 offset:4096
	ds_read_b128 v[20:23], v3 offset:8192
	ds_read_b128 v[24:27], v3 offset:12288
	ds_read_b128 v[28:31], v3 offset:16384
	ds_read_b128 v[32:35], v3 offset:20480
	ds_read_b128 v[36:39], v3 offset:24576
	ds_read_b128 v[40:43], v3 offset:28672
	ds_read_b128 v[44:47], v3
	ds_read_b128 v[48:51], v3 offset:32768
	s_waitcnt lgkmcnt(8)
	v_mov_b32_e32 v61, v16
	s_waitcnt lgkmcnt(7)
	v_mov_b32_e32 v62, v20
	s_waitcnt lgkmcnt(6)
	v_mov_b32_e32 v63, v24
	s_waitcnt lgkmcnt(1)
	v_mov_b32_e32 v60, v44
	v_mov_b32_e32 v64, v28
	v_mov_b32_e32 v65, v32
	v_mov_b32_e32 v66, v36
	v_mov_b32_e32 v67, v40
	v_mov_b32_e32 v16, v45
	v_mov_b32_e32 v24, v21
	v_mov_b32_e32 v32, v29
	v_mov_b32_e32 v40, v37
	v_mov_b32_e32 v20, v46
	v_mov_b32_e32 v21, v18
	v_mov_b32_e32 v28, v22
	v_mov_b32_e32 v29, v26
	v_mov_b32_e32 v36, v30
	v_mov_b32_e32 v37, v34
	v_mov_b32_e32 v44, v38
	v_mov_b32_e32 v45, v42
	v_mov_b32_e32 v18, v47
	v_mov_b32_e32 v26, v23
	v_mov_b32_e32 v34, v31
	v_mov_b32_e32 v42, v39
	v_add_u32_e32 v3, 16, v3
	v_pk_fma_f32 v[6:7], v[52:53], v[60:61], v[6:7] op_sel_hi:[0,1,1]
	v_pk_fma_f32 v[8:9], v[52:53], v[62:63], v[8:9] op_sel_hi:[0,1,1]
	v_pk_fma_f32 v[10:11], v[52:53], v[64:65], v[10:11] op_sel_hi:[0,1,1]
	v_pk_fma_f32 v[12:13], v[52:53], v[66:67], v[12:13] op_sel_hi:[0,1,1]
	s_waitcnt lgkmcnt(0)
	v_fmac_f32_e32 v15, v52, v48
	v_pk_fma_f32 v[6:7], v[54:55], v[16:17], v[6:7] op_sel_hi:[0,1,1]
	v_pk_fma_f32 v[8:9], v[54:55], v[24:25], v[8:9] op_sel_hi:[0,1,1]
	v_pk_fma_f32 v[10:11], v[54:55], v[32:33], v[10:11] op_sel_hi:[0,1,1]
	v_pk_fma_f32 v[12:13], v[54:55], v[40:41], v[12:13] op_sel_hi:[0,1,1]
	v_fmac_f32_e32 v15, v54, v49
	v_pk_fma_f32 v[6:7], v[56:57], v[20:21], v[6:7] op_sel_hi:[0,1,1]
	v_pk_fma_f32 v[8:9], v[56:57], v[28:29], v[8:9] op_sel_hi:[0,1,1]
	v_pk_fma_f32 v[10:11], v[56:57], v[36:37], v[10:11] op_sel_hi:[0,1,1]
	v_pk_fma_f32 v[12:13], v[56:57], v[44:45], v[12:13] op_sel_hi:[0,1,1]
	v_fmac_f32_e32 v15, v56, v50
	v_pk_fma_f32 v[6:7], v[58:59], v[18:19], v[6:7] op_sel_hi:[0,1,1]
	v_pk_fma_f32 v[8:9], v[58:59], v[26:27], v[8:9] op_sel_hi:[0,1,1]
	v_pk_fma_f32 v[10:11], v[58:59], v[34:35], v[10:11] op_sel_hi:[0,1,1]
	v_pk_fma_f32 v[12:13], v[58:59], v[42:43], v[12:13] op_sel_hi:[0,1,1]
	v_fmac_f32_e32 v15, v58, v51
	s_waitcnt vmcnt(60)
	v_mov_b32_e32 v52, v88
	v_mov_b32_e32 v54, v89
	v_mov_b32_e32 v56, v90
	v_mov_b32_e32 v58, v91
	global_load_dword v88, v[144:145], off
	v_add_co_u32_e32 v144, vcc, s33, v144
	s_nop 1
	v_addc_co_u32_e32 v145, vcc, 0, v145, vcc
	global_load_dword v89, v[144:145], off
	v_add_co_u32_e32 v144, vcc, s33, v144
	s_nop 1
	v_addc_co_u32_e32 v145, vcc, 0, v145, vcc
	global_load_dword v90, v[144:145], off
	v_add_co_u32_e32 v144, vcc, s33, v144
	s_nop 1
	v_addc_co_u32_e32 v145, vcc, 0, v145, vcc
	global_load_dword v91, v[144:145], off
	v_add_co_u32_e32 v144, vcc, s33, v144
	s_nop 1
	v_addc_co_u32_e32 v145, vcc, 0, v145, vcc
	ds_read_b128 v[16:19], v3 offset:4096
	ds_read_b128 v[20:23], v3 offset:8192
	ds_read_b128 v[24:27], v3 offset:12288
	ds_read_b128 v[28:31], v3 offset:16384
	ds_read_b128 v[32:35], v3 offset:20480
	ds_read_b128 v[36:39], v3 offset:24576
	ds_read_b128 v[40:43], v3 offset:28672
	ds_read_b128 v[44:47], v3
	ds_read_b128 v[48:51], v3 offset:32768
	s_waitcnt lgkmcnt(8)
	v_mov_b32_e32 v61, v16
	s_waitcnt lgkmcnt(7)
	v_mov_b32_e32 v62, v20
	s_waitcnt lgkmcnt(6)
	v_mov_b32_e32 v63, v24
	s_waitcnt lgkmcnt(1)
	v_mov_b32_e32 v60, v44
	v_mov_b32_e32 v64, v28
	v_mov_b32_e32 v65, v32
	v_mov_b32_e32 v66, v36
	v_mov_b32_e32 v67, v40
	v_mov_b32_e32 v16, v45
	v_mov_b32_e32 v24, v21
	v_mov_b32_e32 v32, v29
	v_mov_b32_e32 v40, v37
	v_mov_b32_e32 v20, v46
	v_mov_b32_e32 v21, v18
	v_mov_b32_e32 v28, v22
	v_mov_b32_e32 v29, v26
	v_mov_b32_e32 v36, v30
	v_mov_b32_e32 v37, v34
	v_mov_b32_e32 v44, v38
	v_mov_b32_e32 v45, v42
	v_mov_b32_e32 v18, v47
	v_mov_b32_e32 v26, v23
	v_mov_b32_e32 v34, v31
	v_mov_b32_e32 v42, v39
	v_add_u32_e32 v3, 16, v3
	v_pk_fma_f32 v[6:7], v[52:53], v[60:61], v[6:7] op_sel_hi:[0,1,1]
	v_pk_fma_f32 v[8:9], v[52:53], v[62:63], v[8:9] op_sel_hi:[0,1,1]
	v_pk_fma_f32 v[10:11], v[52:53], v[64:65], v[10:11] op_sel_hi:[0,1,1]
	v_pk_fma_f32 v[12:13], v[52:53], v[66:67], v[12:13] op_sel_hi:[0,1,1]
	s_waitcnt lgkmcnt(0)
	v_fmac_f32_e32 v15, v52, v48
	v_pk_fma_f32 v[6:7], v[54:55], v[16:17], v[6:7] op_sel_hi:[0,1,1]
	v_pk_fma_f32 v[8:9], v[54:55], v[24:25], v[8:9] op_sel_hi:[0,1,1]
	v_pk_fma_f32 v[10:11], v[54:55], v[32:33], v[10:11] op_sel_hi:[0,1,1]
	v_pk_fma_f32 v[12:13], v[54:55], v[40:41], v[12:13] op_sel_hi:[0,1,1]
	v_fmac_f32_e32 v15, v54, v49
	v_pk_fma_f32 v[6:7], v[56:57], v[20:21], v[6:7] op_sel_hi:[0,1,1]
	v_pk_fma_f32 v[8:9], v[56:57], v[28:29], v[8:9] op_sel_hi:[0,1,1]
	v_pk_fma_f32 v[10:11], v[56:57], v[36:37], v[10:11] op_sel_hi:[0,1,1]
	v_pk_fma_f32 v[12:13], v[56:57], v[44:45], v[12:13] op_sel_hi:[0,1,1]
	v_fmac_f32_e32 v15, v56, v50
	v_pk_fma_f32 v[6:7], v[58:59], v[18:19], v[6:7] op_sel_hi:[0,1,1]
	v_pk_fma_f32 v[8:9], v[58:59], v[26:27], v[8:9] op_sel_hi:[0,1,1]
	v_pk_fma_f32 v[10:11], v[58:59], v[34:35], v[10:11] op_sel_hi:[0,1,1]
	v_pk_fma_f32 v[12:13], v[58:59], v[42:43], v[12:13] op_sel_hi:[0,1,1]
	v_fmac_f32_e32 v15, v58, v51
	s_waitcnt vmcnt(60)
	v_mov_b32_e32 v52, v92
	v_mov_b32_e32 v54, v93
	v_mov_b32_e32 v56, v94
	v_mov_b32_e32 v58, v95
	global_load_dword v92, v[144:145], off
	v_add_co_u32_e32 v144, vcc, s33, v144
	s_nop 1
	v_addc_co_u32_e32 v145, vcc, 0, v145, vcc
	global_load_dword v93, v[144:145], off
	v_add_co_u32_e32 v144, vcc, s33, v144
	s_nop 1
	v_addc_co_u32_e32 v145, vcc, 0, v145, vcc
	global_load_dword v94, v[144:145], off
	v_add_co_u32_e32 v144, vcc, s33, v144
	s_nop 1
	v_addc_co_u32_e32 v145, vcc, 0, v145, vcc
	global_load_dword v95, v[144:145], off
	v_add_co_u32_e32 v144, vcc, s33, v144
	s_nop 1
	v_addc_co_u32_e32 v145, vcc, 0, v145, vcc
	ds_read_b128 v[16:19], v3 offset:4096
	ds_read_b128 v[20:23], v3 offset:8192
	ds_read_b128 v[24:27], v3 offset:12288
	ds_read_b128 v[28:31], v3 offset:16384
	ds_read_b128 v[32:35], v3 offset:20480
	ds_read_b128 v[36:39], v3 offset:24576
	ds_read_b128 v[40:43], v3 offset:28672
	ds_read_b128 v[44:47], v3
	ds_read_b128 v[48:51], v3 offset:32768
	s_waitcnt lgkmcnt(8)
	v_mov_b32_e32 v61, v16
	s_waitcnt lgkmcnt(7)
	v_mov_b32_e32 v62, v20
	s_waitcnt lgkmcnt(6)
	v_mov_b32_e32 v63, v24
	s_waitcnt lgkmcnt(1)
	v_mov_b32_e32 v60, v44
	v_mov_b32_e32 v64, v28
	v_mov_b32_e32 v65, v32
	v_mov_b32_e32 v66, v36
	v_mov_b32_e32 v67, v40
	v_mov_b32_e32 v16, v45
	v_mov_b32_e32 v24, v21
	v_mov_b32_e32 v32, v29
	v_mov_b32_e32 v40, v37
	v_mov_b32_e32 v20, v46
	v_mov_b32_e32 v21, v18
	v_mov_b32_e32 v28, v22
	v_mov_b32_e32 v29, v26
	v_mov_b32_e32 v36, v30
	v_mov_b32_e32 v37, v34
	v_mov_b32_e32 v44, v38
	v_mov_b32_e32 v45, v42
	v_mov_b32_e32 v18, v47
	v_mov_b32_e32 v26, v23
	v_mov_b32_e32 v34, v31
	v_mov_b32_e32 v42, v39
	v_add_u32_e32 v3, 16, v3
	v_pk_fma_f32 v[6:7], v[52:53], v[60:61], v[6:7] op_sel_hi:[0,1,1]
	v_pk_fma_f32 v[8:9], v[52:53], v[62:63], v[8:9] op_sel_hi:[0,1,1]
	v_pk_fma_f32 v[10:11], v[52:53], v[64:65], v[10:11] op_sel_hi:[0,1,1]
	v_pk_fma_f32 v[12:13], v[52:53], v[66:67], v[12:13] op_sel_hi:[0,1,1]
	s_waitcnt lgkmcnt(0)
	v_fmac_f32_e32 v15, v52, v48
	v_pk_fma_f32 v[6:7], v[54:55], v[16:17], v[6:7] op_sel_hi:[0,1,1]
	v_pk_fma_f32 v[8:9], v[54:55], v[24:25], v[8:9] op_sel_hi:[0,1,1]
	v_pk_fma_f32 v[10:11], v[54:55], v[32:33], v[10:11] op_sel_hi:[0,1,1]
	v_pk_fma_f32 v[12:13], v[54:55], v[40:41], v[12:13] op_sel_hi:[0,1,1]
	v_fmac_f32_e32 v15, v54, v49
	v_pk_fma_f32 v[6:7], v[56:57], v[20:21], v[6:7] op_sel_hi:[0,1,1]
	v_pk_fma_f32 v[8:9], v[56:57], v[28:29], v[8:9] op_sel_hi:[0,1,1]
	v_pk_fma_f32 v[10:11], v[56:57], v[36:37], v[10:11] op_sel_hi:[0,1,1]
	v_pk_fma_f32 v[12:13], v[56:57], v[44:45], v[12:13] op_sel_hi:[0,1,1]
	v_fmac_f32_e32 v15, v56, v50
	v_pk_fma_f32 v[6:7], v[58:59], v[18:19], v[6:7] op_sel_hi:[0,1,1]
	v_pk_fma_f32 v[8:9], v[58:59], v[26:27], v[8:9] op_sel_hi:[0,1,1]
	v_pk_fma_f32 v[10:11], v[58:59], v[34:35], v[10:11] op_sel_hi:[0,1,1]
	v_pk_fma_f32 v[12:13], v[58:59], v[42:43], v[12:13] op_sel_hi:[0,1,1]
	v_fmac_f32_e32 v15, v58, v51
	s_waitcnt vmcnt(60)
	v_mov_b32_e32 v52, v96
	v_mov_b32_e32 v54, v97
	v_mov_b32_e32 v56, v98
	v_mov_b32_e32 v58, v99
	global_load_dword v96, v[144:145], off
	v_add_co_u32_e32 v144, vcc, s33, v144
	s_nop 1
	v_addc_co_u32_e32 v145, vcc, 0, v145, vcc
	global_load_dword v97, v[144:145], off
	v_add_co_u32_e32 v144, vcc, s33, v144
	s_nop 1
	v_addc_co_u32_e32 v145, vcc, 0, v145, vcc
	global_load_dword v98, v[144:145], off
	v_add_co_u32_e32 v144, vcc, s33, v144
	s_nop 1
	v_addc_co_u32_e32 v145, vcc, 0, v145, vcc
	global_load_dword v99, v[144:145], off
	v_add_co_u32_e32 v144, vcc, s33, v144
	s_nop 1
	v_addc_co_u32_e32 v145, vcc, 0, v145, vcc
	ds_read_b128 v[16:19], v3 offset:4096
	ds_read_b128 v[20:23], v3 offset:8192
	ds_read_b128 v[24:27], v3 offset:12288
	ds_read_b128 v[28:31], v3 offset:16384
	ds_read_b128 v[32:35], v3 offset:20480
	ds_read_b128 v[36:39], v3 offset:24576
	ds_read_b128 v[40:43], v3 offset:28672
	ds_read_b128 v[44:47], v3
	ds_read_b128 v[48:51], v3 offset:32768
	s_waitcnt lgkmcnt(8)
	v_mov_b32_e32 v61, v16
	s_waitcnt lgkmcnt(7)
	v_mov_b32_e32 v62, v20
	s_waitcnt lgkmcnt(6)
	v_mov_b32_e32 v63, v24
	s_waitcnt lgkmcnt(1)
	v_mov_b32_e32 v60, v44
	v_mov_b32_e32 v64, v28
	v_mov_b32_e32 v65, v32
	v_mov_b32_e32 v66, v36
	v_mov_b32_e32 v67, v40
	v_mov_b32_e32 v16, v45
	v_mov_b32_e32 v24, v21
	v_mov_b32_e32 v32, v29
	v_mov_b32_e32 v40, v37
	v_mov_b32_e32 v20, v46
	v_mov_b32_e32 v21, v18
	v_mov_b32_e32 v28, v22
	v_mov_b32_e32 v29, v26
	v_mov_b32_e32 v36, v30
	v_mov_b32_e32 v37, v34
	v_mov_b32_e32 v44, v38
	v_mov_b32_e32 v45, v42
	v_mov_b32_e32 v18, v47
	v_mov_b32_e32 v26, v23
	v_mov_b32_e32 v34, v31
	v_mov_b32_e32 v42, v39
	v_add_u32_e32 v3, 16, v3
	v_pk_fma_f32 v[6:7], v[52:53], v[60:61], v[6:7] op_sel_hi:[0,1,1]
	v_pk_fma_f32 v[8:9], v[52:53], v[62:63], v[8:9] op_sel_hi:[0,1,1]
	v_pk_fma_f32 v[10:11], v[52:53], v[64:65], v[10:11] op_sel_hi:[0,1,1]
	v_pk_fma_f32 v[12:13], v[52:53], v[66:67], v[12:13] op_sel_hi:[0,1,1]
	s_waitcnt lgkmcnt(0)
	v_fmac_f32_e32 v15, v52, v48
	v_pk_fma_f32 v[6:7], v[54:55], v[16:17], v[6:7] op_sel_hi:[0,1,1]
	v_pk_fma_f32 v[8:9], v[54:55], v[24:25], v[8:9] op_sel_hi:[0,1,1]
	v_pk_fma_f32 v[10:11], v[54:55], v[32:33], v[10:11] op_sel_hi:[0,1,1]
	v_pk_fma_f32 v[12:13], v[54:55], v[40:41], v[12:13] op_sel_hi:[0,1,1]
	v_fmac_f32_e32 v15, v54, v49
	v_pk_fma_f32 v[6:7], v[56:57], v[20:21], v[6:7] op_sel_hi:[0,1,1]
	v_pk_fma_f32 v[8:9], v[56:57], v[28:29], v[8:9] op_sel_hi:[0,1,1]
	v_pk_fma_f32 v[10:11], v[56:57], v[36:37], v[10:11] op_sel_hi:[0,1,1]
	v_pk_fma_f32 v[12:13], v[56:57], v[44:45], v[12:13] op_sel_hi:[0,1,1]
	v_fmac_f32_e32 v15, v56, v50
	v_pk_fma_f32 v[6:7], v[58:59], v[18:19], v[6:7] op_sel_hi:[0,1,1]
	v_pk_fma_f32 v[8:9], v[58:59], v[26:27], v[8:9] op_sel_hi:[0,1,1]
	v_pk_fma_f32 v[10:11], v[58:59], v[34:35], v[10:11] op_sel_hi:[0,1,1]
	v_pk_fma_f32 v[12:13], v[58:59], v[42:43], v[12:13] op_sel_hi:[0,1,1]
	v_fmac_f32_e32 v15, v58, v51
	s_waitcnt vmcnt(60)
	v_mov_b32_e32 v52, v100
	v_mov_b32_e32 v54, v101
	v_mov_b32_e32 v56, v102
	v_mov_b32_e32 v58, v103
	global_load_dword v100, v[144:145], off
	v_add_co_u32_e32 v144, vcc, s33, v144
	s_nop 1
	v_addc_co_u32_e32 v145, vcc, 0, v145, vcc
	global_load_dword v101, v[144:145], off
	v_add_co_u32_e32 v144, vcc, s33, v144
	s_nop 1
	v_addc_co_u32_e32 v145, vcc, 0, v145, vcc
	global_load_dword v102, v[144:145], off
	v_add_co_u32_e32 v144, vcc, s33, v144
	s_nop 1
	v_addc_co_u32_e32 v145, vcc, 0, v145, vcc
	global_load_dword v103, v[144:145], off
	v_add_co_u32_e32 v144, vcc, s33, v144
	s_nop 1
	v_addc_co_u32_e32 v145, vcc, 0, v145, vcc
	ds_read_b128 v[16:19], v3 offset:4096
	ds_read_b128 v[20:23], v3 offset:8192
	ds_read_b128 v[24:27], v3 offset:12288
	ds_read_b128 v[28:31], v3 offset:16384
	ds_read_b128 v[32:35], v3 offset:20480
	ds_read_b128 v[36:39], v3 offset:24576
	ds_read_b128 v[40:43], v3 offset:28672
	ds_read_b128 v[44:47], v3
	ds_read_b128 v[48:51], v3 offset:32768
	s_waitcnt lgkmcnt(8)
	v_mov_b32_e32 v61, v16
	s_waitcnt lgkmcnt(7)
	v_mov_b32_e32 v62, v20
	s_waitcnt lgkmcnt(6)
	v_mov_b32_e32 v63, v24
	s_waitcnt lgkmcnt(1)
	v_mov_b32_e32 v60, v44
	v_mov_b32_e32 v64, v28
	v_mov_b32_e32 v65, v32
	v_mov_b32_e32 v66, v36
	v_mov_b32_e32 v67, v40
	v_mov_b32_e32 v16, v45
	v_mov_b32_e32 v24, v21
	v_mov_b32_e32 v32, v29
	v_mov_b32_e32 v40, v37
	v_mov_b32_e32 v20, v46
	v_mov_b32_e32 v21, v18
	v_mov_b32_e32 v28, v22
	v_mov_b32_e32 v29, v26
	v_mov_b32_e32 v36, v30
	v_mov_b32_e32 v37, v34
	v_mov_b32_e32 v44, v38
	v_mov_b32_e32 v45, v42
	v_mov_b32_e32 v18, v47
	v_mov_b32_e32 v26, v23
	v_mov_b32_e32 v34, v31
	v_mov_b32_e32 v42, v39
	v_add_u32_e32 v3, 16, v3
	v_pk_fma_f32 v[6:7], v[52:53], v[60:61], v[6:7] op_sel_hi:[0,1,1]
	v_pk_fma_f32 v[8:9], v[52:53], v[62:63], v[8:9] op_sel_hi:[0,1,1]
	v_pk_fma_f32 v[10:11], v[52:53], v[64:65], v[10:11] op_sel_hi:[0,1,1]
	v_pk_fma_f32 v[12:13], v[52:53], v[66:67], v[12:13] op_sel_hi:[0,1,1]
	s_waitcnt lgkmcnt(0)
	v_fmac_f32_e32 v15, v52, v48
	v_pk_fma_f32 v[6:7], v[54:55], v[16:17], v[6:7] op_sel_hi:[0,1,1]
	v_pk_fma_f32 v[8:9], v[54:55], v[24:25], v[8:9] op_sel_hi:[0,1,1]
	v_pk_fma_f32 v[10:11], v[54:55], v[32:33], v[10:11] op_sel_hi:[0,1,1]
	v_pk_fma_f32 v[12:13], v[54:55], v[40:41], v[12:13] op_sel_hi:[0,1,1]
	v_fmac_f32_e32 v15, v54, v49
	v_pk_fma_f32 v[6:7], v[56:57], v[20:21], v[6:7] op_sel_hi:[0,1,1]
	v_pk_fma_f32 v[8:9], v[56:57], v[28:29], v[8:9] op_sel_hi:[0,1,1]
	v_pk_fma_f32 v[10:11], v[56:57], v[36:37], v[10:11] op_sel_hi:[0,1,1]
	v_pk_fma_f32 v[12:13], v[56:57], v[44:45], v[12:13] op_sel_hi:[0,1,1]
	v_fmac_f32_e32 v15, v56, v50
	v_pk_fma_f32 v[6:7], v[58:59], v[18:19], v[6:7] op_sel_hi:[0,1,1]
	v_pk_fma_f32 v[8:9], v[58:59], v[26:27], v[8:9] op_sel_hi:[0,1,1]
	v_pk_fma_f32 v[10:11], v[58:59], v[34:35], v[10:11] op_sel_hi:[0,1,1]
	v_pk_fma_f32 v[12:13], v[58:59], v[42:43], v[12:13] op_sel_hi:[0,1,1]
	v_fmac_f32_e32 v15, v58, v51
	s_waitcnt vmcnt(60)
	v_mov_b32_e32 v52, v104
	v_mov_b32_e32 v54, v105
	v_mov_b32_e32 v56, v106
	v_mov_b32_e32 v58, v107
	global_load_dword v104, v[144:145], off
	v_add_co_u32_e32 v144, vcc, s33, v144
	s_nop 1
	v_addc_co_u32_e32 v145, vcc, 0, v145, vcc
	global_load_dword v105, v[144:145], off
	v_add_co_u32_e32 v144, vcc, s33, v144
	s_nop 1
	v_addc_co_u32_e32 v145, vcc, 0, v145, vcc
	global_load_dword v106, v[144:145], off
	v_add_co_u32_e32 v144, vcc, s33, v144
	s_nop 1
	v_addc_co_u32_e32 v145, vcc, 0, v145, vcc
	global_load_dword v107, v[144:145], off
	v_add_co_u32_e32 v144, vcc, s33, v144
	s_nop 1
	v_addc_co_u32_e32 v145, vcc, 0, v145, vcc
	ds_read_b128 v[16:19], v3 offset:4096
	ds_read_b128 v[20:23], v3 offset:8192
	ds_read_b128 v[24:27], v3 offset:12288
	ds_read_b128 v[28:31], v3 offset:16384
	ds_read_b128 v[32:35], v3 offset:20480
	ds_read_b128 v[36:39], v3 offset:24576
	ds_read_b128 v[40:43], v3 offset:28672
	ds_read_b128 v[44:47], v3
	ds_read_b128 v[48:51], v3 offset:32768
	s_waitcnt lgkmcnt(8)
	v_mov_b32_e32 v61, v16
	s_waitcnt lgkmcnt(7)
	v_mov_b32_e32 v62, v20
	s_waitcnt lgkmcnt(6)
	v_mov_b32_e32 v63, v24
	s_waitcnt lgkmcnt(1)
	v_mov_b32_e32 v60, v44
	v_mov_b32_e32 v64, v28
	v_mov_b32_e32 v65, v32
	v_mov_b32_e32 v66, v36
	v_mov_b32_e32 v67, v40
	v_mov_b32_e32 v16, v45
	v_mov_b32_e32 v24, v21
	v_mov_b32_e32 v32, v29
	v_mov_b32_e32 v40, v37
	v_mov_b32_e32 v20, v46
	v_mov_b32_e32 v21, v18
	v_mov_b32_e32 v28, v22
	v_mov_b32_e32 v29, v26
	v_mov_b32_e32 v36, v30
	v_mov_b32_e32 v37, v34
	v_mov_b32_e32 v44, v38
	v_mov_b32_e32 v45, v42
	v_mov_b32_e32 v18, v47
	v_mov_b32_e32 v26, v23
	v_mov_b32_e32 v34, v31
	v_mov_b32_e32 v42, v39
	v_add_u32_e32 v3, 16, v3
	v_pk_fma_f32 v[6:7], v[52:53], v[60:61], v[6:7] op_sel_hi:[0,1,1]
	v_pk_fma_f32 v[8:9], v[52:53], v[62:63], v[8:9] op_sel_hi:[0,1,1]
	v_pk_fma_f32 v[10:11], v[52:53], v[64:65], v[10:11] op_sel_hi:[0,1,1]
	v_pk_fma_f32 v[12:13], v[52:53], v[66:67], v[12:13] op_sel_hi:[0,1,1]
	s_waitcnt lgkmcnt(0)
	v_fmac_f32_e32 v15, v52, v48
	v_pk_fma_f32 v[6:7], v[54:55], v[16:17], v[6:7] op_sel_hi:[0,1,1]
	v_pk_fma_f32 v[8:9], v[54:55], v[24:25], v[8:9] op_sel_hi:[0,1,1]
	v_pk_fma_f32 v[10:11], v[54:55], v[32:33], v[10:11] op_sel_hi:[0,1,1]
	v_pk_fma_f32 v[12:13], v[54:55], v[40:41], v[12:13] op_sel_hi:[0,1,1]
	v_fmac_f32_e32 v15, v54, v49
	v_pk_fma_f32 v[6:7], v[56:57], v[20:21], v[6:7] op_sel_hi:[0,1,1]
	v_pk_fma_f32 v[8:9], v[56:57], v[28:29], v[8:9] op_sel_hi:[0,1,1]
	v_pk_fma_f32 v[10:11], v[56:57], v[36:37], v[10:11] op_sel_hi:[0,1,1]
	v_pk_fma_f32 v[12:13], v[56:57], v[44:45], v[12:13] op_sel_hi:[0,1,1]
	v_fmac_f32_e32 v15, v56, v50
	v_pk_fma_f32 v[6:7], v[58:59], v[18:19], v[6:7] op_sel_hi:[0,1,1]
	v_pk_fma_f32 v[8:9], v[58:59], v[26:27], v[8:9] op_sel_hi:[0,1,1]
	v_pk_fma_f32 v[10:11], v[58:59], v[34:35], v[10:11] op_sel_hi:[0,1,1]
	v_pk_fma_f32 v[12:13], v[58:59], v[42:43], v[12:13] op_sel_hi:[0,1,1]
	v_fmac_f32_e32 v15, v58, v51
	s_waitcnt vmcnt(60)
	v_mov_b32_e32 v52, v108
	v_mov_b32_e32 v54, v109
	v_mov_b32_e32 v56, v110
	v_mov_b32_e32 v58, v111
	global_load_dword v108, v[144:145], off
	v_add_co_u32_e32 v144, vcc, s33, v144
	s_nop 1
	v_addc_co_u32_e32 v145, vcc, 0, v145, vcc
	global_load_dword v109, v[144:145], off
	v_add_co_u32_e32 v144, vcc, s33, v144
	s_nop 1
	v_addc_co_u32_e32 v145, vcc, 0, v145, vcc
	global_load_dword v110, v[144:145], off
	v_add_co_u32_e32 v144, vcc, s33, v144
	s_nop 1
	v_addc_co_u32_e32 v145, vcc, 0, v145, vcc
	global_load_dword v111, v[144:145], off
	v_add_co_u32_e32 v144, vcc, s33, v144
	s_nop 1
	v_addc_co_u32_e32 v145, vcc, 0, v145, vcc
	ds_read_b128 v[16:19], v3 offset:4096
	ds_read_b128 v[20:23], v3 offset:8192
	ds_read_b128 v[24:27], v3 offset:12288
	ds_read_b128 v[28:31], v3 offset:16384
	ds_read_b128 v[32:35], v3 offset:20480
	ds_read_b128 v[36:39], v3 offset:24576
	ds_read_b128 v[40:43], v3 offset:28672
	ds_read_b128 v[44:47], v3
	ds_read_b128 v[48:51], v3 offset:32768
	s_waitcnt lgkmcnt(8)
	v_mov_b32_e32 v61, v16
	s_waitcnt lgkmcnt(7)
	v_mov_b32_e32 v62, v20
	s_waitcnt lgkmcnt(6)
	v_mov_b32_e32 v63, v24
	s_waitcnt lgkmcnt(1)
	v_mov_b32_e32 v60, v44
	v_mov_b32_e32 v64, v28
	v_mov_b32_e32 v65, v32
	v_mov_b32_e32 v66, v36
	v_mov_b32_e32 v67, v40
	v_mov_b32_e32 v16, v45
	v_mov_b32_e32 v24, v21
	v_mov_b32_e32 v32, v29
	v_mov_b32_e32 v40, v37
	v_mov_b32_e32 v20, v46
	v_mov_b32_e32 v21, v18
	v_mov_b32_e32 v28, v22
	v_mov_b32_e32 v29, v26
	v_mov_b32_e32 v36, v30
	v_mov_b32_e32 v37, v34
	v_mov_b32_e32 v44, v38
	v_mov_b32_e32 v45, v42
	v_mov_b32_e32 v18, v47
	v_mov_b32_e32 v26, v23
	v_mov_b32_e32 v34, v31
	v_mov_b32_e32 v42, v39
	v_add_u32_e32 v3, 16, v3
	v_pk_fma_f32 v[6:7], v[52:53], v[60:61], v[6:7] op_sel_hi:[0,1,1]
	v_pk_fma_f32 v[8:9], v[52:53], v[62:63], v[8:9] op_sel_hi:[0,1,1]
	v_pk_fma_f32 v[10:11], v[52:53], v[64:65], v[10:11] op_sel_hi:[0,1,1]
	v_pk_fma_f32 v[12:13], v[52:53], v[66:67], v[12:13] op_sel_hi:[0,1,1]
	s_waitcnt lgkmcnt(0)
	v_fmac_f32_e32 v15, v52, v48
	v_pk_fma_f32 v[6:7], v[54:55], v[16:17], v[6:7] op_sel_hi:[0,1,1]
	v_pk_fma_f32 v[8:9], v[54:55], v[24:25], v[8:9] op_sel_hi:[0,1,1]
	v_pk_fma_f32 v[10:11], v[54:55], v[32:33], v[10:11] op_sel_hi:[0,1,1]
	v_pk_fma_f32 v[12:13], v[54:55], v[40:41], v[12:13] op_sel_hi:[0,1,1]
	v_fmac_f32_e32 v15, v54, v49
	v_pk_fma_f32 v[6:7], v[56:57], v[20:21], v[6:7] op_sel_hi:[0,1,1]
	v_pk_fma_f32 v[8:9], v[56:57], v[28:29], v[8:9] op_sel_hi:[0,1,1]
	v_pk_fma_f32 v[10:11], v[56:57], v[36:37], v[10:11] op_sel_hi:[0,1,1]
	v_pk_fma_f32 v[12:13], v[56:57], v[44:45], v[12:13] op_sel_hi:[0,1,1]
	v_fmac_f32_e32 v15, v56, v50
	v_pk_fma_f32 v[6:7], v[58:59], v[18:19], v[6:7] op_sel_hi:[0,1,1]
	v_pk_fma_f32 v[8:9], v[58:59], v[26:27], v[8:9] op_sel_hi:[0,1,1]
	v_pk_fma_f32 v[10:11], v[58:59], v[34:35], v[10:11] op_sel_hi:[0,1,1]
	v_pk_fma_f32 v[12:13], v[58:59], v[42:43], v[12:13] op_sel_hi:[0,1,1]
	v_fmac_f32_e32 v15, v58, v51
	s_waitcnt vmcnt(60)
	v_mov_b32_e32 v52, v112
	v_mov_b32_e32 v54, v113
	v_mov_b32_e32 v56, v114
	v_mov_b32_e32 v58, v115
	global_load_dword v112, v[144:145], off
	v_add_co_u32_e32 v144, vcc, s33, v144
	s_nop 1
	v_addc_co_u32_e32 v145, vcc, 0, v145, vcc
	global_load_dword v113, v[144:145], off
	v_add_co_u32_e32 v144, vcc, s33, v144
	s_nop 1
	v_addc_co_u32_e32 v145, vcc, 0, v145, vcc
	global_load_dword v114, v[144:145], off
	v_add_co_u32_e32 v144, vcc, s33, v144
	s_nop 1
	v_addc_co_u32_e32 v145, vcc, 0, v145, vcc
	global_load_dword v115, v[144:145], off
	v_add_co_u32_e32 v144, vcc, s33, v144
	s_nop 1
	v_addc_co_u32_e32 v145, vcc, 0, v145, vcc
	ds_read_b128 v[16:19], v3 offset:4096
	ds_read_b128 v[20:23], v3 offset:8192
	ds_read_b128 v[24:27], v3 offset:12288
	ds_read_b128 v[28:31], v3 offset:16384
	ds_read_b128 v[32:35], v3 offset:20480
	ds_read_b128 v[36:39], v3 offset:24576
	ds_read_b128 v[40:43], v3 offset:28672
	ds_read_b128 v[44:47], v3
	ds_read_b128 v[48:51], v3 offset:32768
	s_waitcnt lgkmcnt(8)
	v_mov_b32_e32 v61, v16
	s_waitcnt lgkmcnt(7)
	v_mov_b32_e32 v62, v20
	s_waitcnt lgkmcnt(6)
	v_mov_b32_e32 v63, v24
	s_waitcnt lgkmcnt(1)
	v_mov_b32_e32 v60, v44
	v_mov_b32_e32 v64, v28
	v_mov_b32_e32 v65, v32
	v_mov_b32_e32 v66, v36
	v_mov_b32_e32 v67, v40
	v_mov_b32_e32 v16, v45
	v_mov_b32_e32 v24, v21
	v_mov_b32_e32 v32, v29
	v_mov_b32_e32 v40, v37
	v_mov_b32_e32 v20, v46
	v_mov_b32_e32 v21, v18
	v_mov_b32_e32 v28, v22
	v_mov_b32_e32 v29, v26
	v_mov_b32_e32 v36, v30
	v_mov_b32_e32 v37, v34
	v_mov_b32_e32 v44, v38
	v_mov_b32_e32 v45, v42
	v_mov_b32_e32 v18, v47
	v_mov_b32_e32 v26, v23
	v_mov_b32_e32 v34, v31
	v_mov_b32_e32 v42, v39
	v_add_u32_e32 v3, 16, v3
	v_pk_fma_f32 v[6:7], v[52:53], v[60:61], v[6:7] op_sel_hi:[0,1,1]
	v_pk_fma_f32 v[8:9], v[52:53], v[62:63], v[8:9] op_sel_hi:[0,1,1]
	v_pk_fma_f32 v[10:11], v[52:53], v[64:65], v[10:11] op_sel_hi:[0,1,1]
	v_pk_fma_f32 v[12:13], v[52:53], v[66:67], v[12:13] op_sel_hi:[0,1,1]
	s_waitcnt lgkmcnt(0)
	v_fmac_f32_e32 v15, v52, v48
	v_pk_fma_f32 v[6:7], v[54:55], v[16:17], v[6:7] op_sel_hi:[0,1,1]
	v_pk_fma_f32 v[8:9], v[54:55], v[24:25], v[8:9] op_sel_hi:[0,1,1]
	v_pk_fma_f32 v[10:11], v[54:55], v[32:33], v[10:11] op_sel_hi:[0,1,1]
	v_pk_fma_f32 v[12:13], v[54:55], v[40:41], v[12:13] op_sel_hi:[0,1,1]
	v_fmac_f32_e32 v15, v54, v49
	v_pk_fma_f32 v[6:7], v[56:57], v[20:21], v[6:7] op_sel_hi:[0,1,1]
	v_pk_fma_f32 v[8:9], v[56:57], v[28:29], v[8:9] op_sel_hi:[0,1,1]
	v_pk_fma_f32 v[10:11], v[56:57], v[36:37], v[10:11] op_sel_hi:[0,1,1]
	v_pk_fma_f32 v[12:13], v[56:57], v[44:45], v[12:13] op_sel_hi:[0,1,1]
	v_fmac_f32_e32 v15, v56, v50
	v_pk_fma_f32 v[6:7], v[58:59], v[18:19], v[6:7] op_sel_hi:[0,1,1]
	v_pk_fma_f32 v[8:9], v[58:59], v[26:27], v[8:9] op_sel_hi:[0,1,1]
	v_pk_fma_f32 v[10:11], v[58:59], v[34:35], v[10:11] op_sel_hi:[0,1,1]
	v_pk_fma_f32 v[12:13], v[58:59], v[42:43], v[12:13] op_sel_hi:[0,1,1]
	v_fmac_f32_e32 v15, v58, v51
	s_waitcnt vmcnt(60)
	v_mov_b32_e32 v52, v116
	v_mov_b32_e32 v54, v117
	v_mov_b32_e32 v56, v118
	v_mov_b32_e32 v58, v119
	global_load_dword v116, v[144:145], off
	v_add_co_u32_e32 v144, vcc, s33, v144
	s_nop 1
	v_addc_co_u32_e32 v145, vcc, 0, v145, vcc
	global_load_dword v117, v[144:145], off
	v_add_co_u32_e32 v144, vcc, s33, v144
	s_nop 1
	v_addc_co_u32_e32 v145, vcc, 0, v145, vcc
	global_load_dword v118, v[144:145], off
	v_add_co_u32_e32 v144, vcc, s33, v144
	s_nop 1
	v_addc_co_u32_e32 v145, vcc, 0, v145, vcc
	global_load_dword v119, v[144:145], off
	v_add_co_u32_e32 v144, vcc, s33, v144
	s_nop 1
	v_addc_co_u32_e32 v145, vcc, 0, v145, vcc
	ds_read_b128 v[16:19], v3 offset:4096
	ds_read_b128 v[20:23], v3 offset:8192
	ds_read_b128 v[24:27], v3 offset:12288
	ds_read_b128 v[28:31], v3 offset:16384
	ds_read_b128 v[32:35], v3 offset:20480
	ds_read_b128 v[36:39], v3 offset:24576
	ds_read_b128 v[40:43], v3 offset:28672
	ds_read_b128 v[44:47], v3
	ds_read_b128 v[48:51], v3 offset:32768
	s_waitcnt lgkmcnt(8)
	v_mov_b32_e32 v61, v16
	s_waitcnt lgkmcnt(7)
	v_mov_b32_e32 v62, v20
	s_waitcnt lgkmcnt(6)
	v_mov_b32_e32 v63, v24
	s_waitcnt lgkmcnt(1)
	v_mov_b32_e32 v60, v44
	v_mov_b32_e32 v64, v28
	v_mov_b32_e32 v65, v32
	v_mov_b32_e32 v66, v36
	v_mov_b32_e32 v67, v40
	v_mov_b32_e32 v16, v45
	v_mov_b32_e32 v24, v21
	v_mov_b32_e32 v32, v29
	v_mov_b32_e32 v40, v37
	v_mov_b32_e32 v20, v46
	v_mov_b32_e32 v21, v18
	v_mov_b32_e32 v28, v22
	v_mov_b32_e32 v29, v26
	v_mov_b32_e32 v36, v30
	v_mov_b32_e32 v37, v34
	v_mov_b32_e32 v44, v38
	v_mov_b32_e32 v45, v42
	v_mov_b32_e32 v18, v47
	v_mov_b32_e32 v26, v23
	v_mov_b32_e32 v34, v31
	v_mov_b32_e32 v42, v39
	v_add_u32_e32 v3, 16, v3
	v_pk_fma_f32 v[6:7], v[52:53], v[60:61], v[6:7] op_sel_hi:[0,1,1]
	v_pk_fma_f32 v[8:9], v[52:53], v[62:63], v[8:9] op_sel_hi:[0,1,1]
	v_pk_fma_f32 v[10:11], v[52:53], v[64:65], v[10:11] op_sel_hi:[0,1,1]
	v_pk_fma_f32 v[12:13], v[52:53], v[66:67], v[12:13] op_sel_hi:[0,1,1]
	s_waitcnt lgkmcnt(0)
	v_fmac_f32_e32 v15, v52, v48
	v_pk_fma_f32 v[6:7], v[54:55], v[16:17], v[6:7] op_sel_hi:[0,1,1]
	v_pk_fma_f32 v[8:9], v[54:55], v[24:25], v[8:9] op_sel_hi:[0,1,1]
	v_pk_fma_f32 v[10:11], v[54:55], v[32:33], v[10:11] op_sel_hi:[0,1,1]
	v_pk_fma_f32 v[12:13], v[54:55], v[40:41], v[12:13] op_sel_hi:[0,1,1]
	v_fmac_f32_e32 v15, v54, v49
	v_pk_fma_f32 v[6:7], v[56:57], v[20:21], v[6:7] op_sel_hi:[0,1,1]
	v_pk_fma_f32 v[8:9], v[56:57], v[28:29], v[8:9] op_sel_hi:[0,1,1]
	v_pk_fma_f32 v[10:11], v[56:57], v[36:37], v[10:11] op_sel_hi:[0,1,1]
	v_pk_fma_f32 v[12:13], v[56:57], v[44:45], v[12:13] op_sel_hi:[0,1,1]
	v_fmac_f32_e32 v15, v56, v50
	v_pk_fma_f32 v[6:7], v[58:59], v[18:19], v[6:7] op_sel_hi:[0,1,1]
	v_pk_fma_f32 v[8:9], v[58:59], v[26:27], v[8:9] op_sel_hi:[0,1,1]
	v_pk_fma_f32 v[10:11], v[58:59], v[34:35], v[10:11] op_sel_hi:[0,1,1]
	v_pk_fma_f32 v[12:13], v[58:59], v[42:43], v[12:13] op_sel_hi:[0,1,1]
	v_fmac_f32_e32 v15, v58, v51
	s_waitcnt vmcnt(60)
	v_mov_b32_e32 v52, v120
	v_mov_b32_e32 v54, v121
	v_mov_b32_e32 v56, v122
	v_mov_b32_e32 v58, v123
	global_load_dword v120, v[144:145], off
	v_add_co_u32_e32 v144, vcc, s33, v144
	s_nop 1
	v_addc_co_u32_e32 v145, vcc, 0, v145, vcc
	global_load_dword v121, v[144:145], off
	v_add_co_u32_e32 v144, vcc, s33, v144
	s_nop 1
	v_addc_co_u32_e32 v145, vcc, 0, v145, vcc
	global_load_dword v122, v[144:145], off
	v_add_co_u32_e32 v144, vcc, s33, v144
	s_nop 1
	v_addc_co_u32_e32 v145, vcc, 0, v145, vcc
	global_load_dword v123, v[144:145], off
	v_add_co_u32_e32 v144, vcc, s33, v144
	s_nop 1
	v_addc_co_u32_e32 v145, vcc, 0, v145, vcc
	ds_read_b128 v[16:19], v3 offset:4096
	ds_read_b128 v[20:23], v3 offset:8192
	ds_read_b128 v[24:27], v3 offset:12288
	ds_read_b128 v[28:31], v3 offset:16384
	ds_read_b128 v[32:35], v3 offset:20480
	ds_read_b128 v[36:39], v3 offset:24576
	ds_read_b128 v[40:43], v3 offset:28672
	ds_read_b128 v[44:47], v3
	ds_read_b128 v[48:51], v3 offset:32768
	s_waitcnt lgkmcnt(8)
	v_mov_b32_e32 v61, v16
	s_waitcnt lgkmcnt(7)
	v_mov_b32_e32 v62, v20
	s_waitcnt lgkmcnt(6)
	v_mov_b32_e32 v63, v24
	s_waitcnt lgkmcnt(1)
	v_mov_b32_e32 v60, v44
	v_mov_b32_e32 v64, v28
	v_mov_b32_e32 v65, v32
	v_mov_b32_e32 v66, v36
	v_mov_b32_e32 v67, v40
	v_mov_b32_e32 v16, v45
	v_mov_b32_e32 v24, v21
	v_mov_b32_e32 v32, v29
	v_mov_b32_e32 v40, v37
	v_mov_b32_e32 v20, v46
	v_mov_b32_e32 v21, v18
	v_mov_b32_e32 v28, v22
	v_mov_b32_e32 v29, v26
	v_mov_b32_e32 v36, v30
	v_mov_b32_e32 v37, v34
	v_mov_b32_e32 v44, v38
	v_mov_b32_e32 v45, v42
	v_mov_b32_e32 v18, v47
	v_mov_b32_e32 v26, v23
	v_mov_b32_e32 v34, v31
	v_mov_b32_e32 v42, v39
	v_add_u32_e32 v3, 16, v3
	v_pk_fma_f32 v[6:7], v[52:53], v[60:61], v[6:7] op_sel_hi:[0,1,1]
	v_pk_fma_f32 v[8:9], v[52:53], v[62:63], v[8:9] op_sel_hi:[0,1,1]
	v_pk_fma_f32 v[10:11], v[52:53], v[64:65], v[10:11] op_sel_hi:[0,1,1]
	v_pk_fma_f32 v[12:13], v[52:53], v[66:67], v[12:13] op_sel_hi:[0,1,1]
	s_waitcnt lgkmcnt(0)
	v_fmac_f32_e32 v15, v52, v48
	v_pk_fma_f32 v[6:7], v[54:55], v[16:17], v[6:7] op_sel_hi:[0,1,1]
	v_pk_fma_f32 v[8:9], v[54:55], v[24:25], v[8:9] op_sel_hi:[0,1,1]
	v_pk_fma_f32 v[10:11], v[54:55], v[32:33], v[10:11] op_sel_hi:[0,1,1]
	v_pk_fma_f32 v[12:13], v[54:55], v[40:41], v[12:13] op_sel_hi:[0,1,1]
	v_fmac_f32_e32 v15, v54, v49
	v_pk_fma_f32 v[6:7], v[56:57], v[20:21], v[6:7] op_sel_hi:[0,1,1]
	v_pk_fma_f32 v[8:9], v[56:57], v[28:29], v[8:9] op_sel_hi:[0,1,1]
	v_pk_fma_f32 v[10:11], v[56:57], v[36:37], v[10:11] op_sel_hi:[0,1,1]
	v_pk_fma_f32 v[12:13], v[56:57], v[44:45], v[12:13] op_sel_hi:[0,1,1]
	v_fmac_f32_e32 v15, v56, v50
	v_pk_fma_f32 v[6:7], v[58:59], v[18:19], v[6:7] op_sel_hi:[0,1,1]
	v_pk_fma_f32 v[8:9], v[58:59], v[26:27], v[8:9] op_sel_hi:[0,1,1]
	v_pk_fma_f32 v[10:11], v[58:59], v[34:35], v[10:11] op_sel_hi:[0,1,1]
	v_pk_fma_f32 v[12:13], v[58:59], v[42:43], v[12:13] op_sel_hi:[0,1,1]
	v_fmac_f32_e32 v15, v58, v51
	s_waitcnt vmcnt(60)
	v_mov_b32_e32 v52, v124
	v_mov_b32_e32 v54, v125
	v_mov_b32_e32 v56, v126
	v_mov_b32_e32 v58, v127
	global_load_dword v124, v[144:145], off
	v_add_co_u32_e32 v144, vcc, s33, v144
	s_nop 1
	v_addc_co_u32_e32 v145, vcc, 0, v145, vcc
	global_load_dword v125, v[144:145], off
	v_add_co_u32_e32 v144, vcc, s33, v144
	s_nop 1
	v_addc_co_u32_e32 v145, vcc, 0, v145, vcc
	global_load_dword v126, v[144:145], off
	v_add_co_u32_e32 v144, vcc, s33, v144
	s_nop 1
	v_addc_co_u32_e32 v145, vcc, 0, v145, vcc
	global_load_dword v127, v[144:145], off
	v_add_co_u32_e32 v144, vcc, s33, v144
	s_nop 1
	v_addc_co_u32_e32 v145, vcc, 0, v145, vcc
	ds_read_b128 v[16:19], v3 offset:4096
	ds_read_b128 v[20:23], v3 offset:8192
	ds_read_b128 v[24:27], v3 offset:12288
	ds_read_b128 v[28:31], v3 offset:16384
	ds_read_b128 v[32:35], v3 offset:20480
	ds_read_b128 v[36:39], v3 offset:24576
	ds_read_b128 v[40:43], v3 offset:28672
	ds_read_b128 v[44:47], v3
	ds_read_b128 v[48:51], v3 offset:32768
	s_waitcnt lgkmcnt(8)
	v_mov_b32_e32 v61, v16
	s_waitcnt lgkmcnt(7)
	v_mov_b32_e32 v62, v20
	s_waitcnt lgkmcnt(6)
	v_mov_b32_e32 v63, v24
	s_waitcnt lgkmcnt(1)
	v_mov_b32_e32 v60, v44
	v_mov_b32_e32 v64, v28
	v_mov_b32_e32 v65, v32
	v_mov_b32_e32 v66, v36
	v_mov_b32_e32 v67, v40
	v_mov_b32_e32 v16, v45
	v_mov_b32_e32 v24, v21
	v_mov_b32_e32 v32, v29
	v_mov_b32_e32 v40, v37
	v_mov_b32_e32 v20, v46
	v_mov_b32_e32 v21, v18
	v_mov_b32_e32 v28, v22
	v_mov_b32_e32 v29, v26
	v_mov_b32_e32 v36, v30
	v_mov_b32_e32 v37, v34
	v_mov_b32_e32 v44, v38
	v_mov_b32_e32 v45, v42
	v_mov_b32_e32 v18, v47
	v_mov_b32_e32 v26, v23
	v_mov_b32_e32 v34, v31
	v_mov_b32_e32 v42, v39
	v_add_u32_e32 v3, 16, v3
	v_pk_fma_f32 v[6:7], v[52:53], v[60:61], v[6:7] op_sel_hi:[0,1,1]
	v_pk_fma_f32 v[8:9], v[52:53], v[62:63], v[8:9] op_sel_hi:[0,1,1]
	v_pk_fma_f32 v[10:11], v[52:53], v[64:65], v[10:11] op_sel_hi:[0,1,1]
	v_pk_fma_f32 v[12:13], v[52:53], v[66:67], v[12:13] op_sel_hi:[0,1,1]
	s_waitcnt lgkmcnt(0)
	v_fmac_f32_e32 v15, v52, v48
	v_pk_fma_f32 v[6:7], v[54:55], v[16:17], v[6:7] op_sel_hi:[0,1,1]
	v_pk_fma_f32 v[8:9], v[54:55], v[24:25], v[8:9] op_sel_hi:[0,1,1]
	v_pk_fma_f32 v[10:11], v[54:55], v[32:33], v[10:11] op_sel_hi:[0,1,1]
	v_pk_fma_f32 v[12:13], v[54:55], v[40:41], v[12:13] op_sel_hi:[0,1,1]
	v_fmac_f32_e32 v15, v54, v49
	v_pk_fma_f32 v[6:7], v[56:57], v[20:21], v[6:7] op_sel_hi:[0,1,1]
	v_pk_fma_f32 v[8:9], v[56:57], v[28:29], v[8:9] op_sel_hi:[0,1,1]
	v_pk_fma_f32 v[10:11], v[56:57], v[36:37], v[10:11] op_sel_hi:[0,1,1]
	v_pk_fma_f32 v[12:13], v[56:57], v[44:45], v[12:13] op_sel_hi:[0,1,1]
	v_fmac_f32_e32 v15, v56, v50
	v_pk_fma_f32 v[6:7], v[58:59], v[18:19], v[6:7] op_sel_hi:[0,1,1]
	v_pk_fma_f32 v[8:9], v[58:59], v[26:27], v[8:9] op_sel_hi:[0,1,1]
	v_pk_fma_f32 v[10:11], v[58:59], v[34:35], v[10:11] op_sel_hi:[0,1,1]
	v_pk_fma_f32 v[12:13], v[58:59], v[42:43], v[12:13] op_sel_hi:[0,1,1]
	v_fmac_f32_e32 v15, v58, v51
	s_waitcnt vmcnt(60)
	v_mov_b32_e32 v52, v128
	v_mov_b32_e32 v54, v129
	v_mov_b32_e32 v56, v130
	v_mov_b32_e32 v58, v131
	global_load_dword v128, v[144:145], off
	v_add_co_u32_e32 v144, vcc, s33, v144
	s_nop 1
	v_addc_co_u32_e32 v145, vcc, 0, v145, vcc
	global_load_dword v129, v[144:145], off
	v_add_co_u32_e32 v144, vcc, s33, v144
	s_nop 1
	v_addc_co_u32_e32 v145, vcc, 0, v145, vcc
	global_load_dword v130, v[144:145], off
	v_add_co_u32_e32 v144, vcc, s33, v144
	s_nop 1
	v_addc_co_u32_e32 v145, vcc, 0, v145, vcc
	global_load_dword v131, v[144:145], off
	v_add_co_u32_e32 v144, vcc, s33, v144
	s_nop 1
	v_addc_co_u32_e32 v145, vcc, 0, v145, vcc
	ds_read_b128 v[16:19], v3 offset:4096
	ds_read_b128 v[20:23], v3 offset:8192
	ds_read_b128 v[24:27], v3 offset:12288
	ds_read_b128 v[28:31], v3 offset:16384
	ds_read_b128 v[32:35], v3 offset:20480
	ds_read_b128 v[36:39], v3 offset:24576
	ds_read_b128 v[40:43], v3 offset:28672
	ds_read_b128 v[44:47], v3
	ds_read_b128 v[48:51], v3 offset:32768
	s_waitcnt lgkmcnt(8)
	v_mov_b32_e32 v61, v16
	s_waitcnt lgkmcnt(7)
	v_mov_b32_e32 v62, v20
	s_waitcnt lgkmcnt(6)
	v_mov_b32_e32 v63, v24
	s_waitcnt lgkmcnt(1)
	v_mov_b32_e32 v60, v44
	v_mov_b32_e32 v64, v28
	v_mov_b32_e32 v65, v32
	v_mov_b32_e32 v66, v36
	v_mov_b32_e32 v67, v40
	v_mov_b32_e32 v16, v45
	v_mov_b32_e32 v24, v21
	v_mov_b32_e32 v32, v29
	v_mov_b32_e32 v40, v37
	v_mov_b32_e32 v20, v46
	v_mov_b32_e32 v21, v18
	v_mov_b32_e32 v28, v22
	v_mov_b32_e32 v29, v26
	v_mov_b32_e32 v36, v30
	v_mov_b32_e32 v37, v34
	v_mov_b32_e32 v44, v38
	v_mov_b32_e32 v45, v42
	v_mov_b32_e32 v18, v47
	v_mov_b32_e32 v26, v23
	v_mov_b32_e32 v34, v31
	v_mov_b32_e32 v42, v39
	v_add_u32_e32 v3, 16, v3
	v_pk_fma_f32 v[6:7], v[52:53], v[60:61], v[6:7] op_sel_hi:[0,1,1]
	v_pk_fma_f32 v[8:9], v[52:53], v[62:63], v[8:9] op_sel_hi:[0,1,1]
	v_pk_fma_f32 v[10:11], v[52:53], v[64:65], v[10:11] op_sel_hi:[0,1,1]
	v_pk_fma_f32 v[12:13], v[52:53], v[66:67], v[12:13] op_sel_hi:[0,1,1]
	s_waitcnt lgkmcnt(0)
	v_fmac_f32_e32 v15, v52, v48
	v_pk_fma_f32 v[6:7], v[54:55], v[16:17], v[6:7] op_sel_hi:[0,1,1]
	v_pk_fma_f32 v[8:9], v[54:55], v[24:25], v[8:9] op_sel_hi:[0,1,1]
	v_pk_fma_f32 v[10:11], v[54:55], v[32:33], v[10:11] op_sel_hi:[0,1,1]
	v_pk_fma_f32 v[12:13], v[54:55], v[40:41], v[12:13] op_sel_hi:[0,1,1]
	v_fmac_f32_e32 v15, v54, v49
	v_pk_fma_f32 v[6:7], v[56:57], v[20:21], v[6:7] op_sel_hi:[0,1,1]
	v_pk_fma_f32 v[8:9], v[56:57], v[28:29], v[8:9] op_sel_hi:[0,1,1]
	v_pk_fma_f32 v[10:11], v[56:57], v[36:37], v[10:11] op_sel_hi:[0,1,1]
	v_pk_fma_f32 v[12:13], v[56:57], v[44:45], v[12:13] op_sel_hi:[0,1,1]
	v_fmac_f32_e32 v15, v56, v50
	v_pk_fma_f32 v[6:7], v[58:59], v[18:19], v[6:7] op_sel_hi:[0,1,1]
	v_pk_fma_f32 v[8:9], v[58:59], v[26:27], v[8:9] op_sel_hi:[0,1,1]
	v_pk_fma_f32 v[10:11], v[58:59], v[34:35], v[10:11] op_sel_hi:[0,1,1]
	v_pk_fma_f32 v[12:13], v[58:59], v[42:43], v[12:13] op_sel_hi:[0,1,1]
	v_fmac_f32_e32 v15, v58, v51
	s_waitcnt vmcnt(60)
	v_mov_b32_e32 v52, v132
	v_mov_b32_e32 v54, v133
	v_mov_b32_e32 v56, v134
	v_mov_b32_e32 v58, v135
	global_load_dword v132, v[144:145], off
	v_add_co_u32_e32 v144, vcc, s33, v144
	s_nop 1
	v_addc_co_u32_e32 v145, vcc, 0, v145, vcc
	global_load_dword v133, v[144:145], off
	v_add_co_u32_e32 v144, vcc, s33, v144
	s_nop 1
	v_addc_co_u32_e32 v145, vcc, 0, v145, vcc
	global_load_dword v134, v[144:145], off
	v_add_co_u32_e32 v144, vcc, s33, v144
	s_nop 1
	v_addc_co_u32_e32 v145, vcc, 0, v145, vcc
	global_load_dword v135, v[144:145], off
	v_add_co_u32_e32 v144, vcc, s33, v144
	s_nop 1
	v_addc_co_u32_e32 v145, vcc, 0, v145, vcc
	ds_read_b128 v[16:19], v3 offset:4096
	ds_read_b128 v[20:23], v3 offset:8192
	ds_read_b128 v[24:27], v3 offset:12288
	ds_read_b128 v[28:31], v3 offset:16384
	ds_read_b128 v[32:35], v3 offset:20480
	ds_read_b128 v[36:39], v3 offset:24576
	ds_read_b128 v[40:43], v3 offset:28672
	ds_read_b128 v[44:47], v3
	ds_read_b128 v[48:51], v3 offset:32768
	s_waitcnt lgkmcnt(8)
	v_mov_b32_e32 v61, v16
	s_waitcnt lgkmcnt(7)
	v_mov_b32_e32 v62, v20
	s_waitcnt lgkmcnt(6)
	v_mov_b32_e32 v63, v24
	s_waitcnt lgkmcnt(1)
	v_mov_b32_e32 v60, v44
	v_mov_b32_e32 v64, v28
	v_mov_b32_e32 v65, v32
	v_mov_b32_e32 v66, v36
	v_mov_b32_e32 v67, v40
	v_mov_b32_e32 v16, v45
	v_mov_b32_e32 v24, v21
	v_mov_b32_e32 v32, v29
	v_mov_b32_e32 v40, v37
	v_mov_b32_e32 v20, v46
	v_mov_b32_e32 v21, v18
	v_mov_b32_e32 v28, v22
	v_mov_b32_e32 v29, v26
	v_mov_b32_e32 v36, v30
	v_mov_b32_e32 v37, v34
	v_mov_b32_e32 v44, v38
	v_mov_b32_e32 v45, v42
	v_mov_b32_e32 v18, v47
	v_mov_b32_e32 v26, v23
	v_mov_b32_e32 v34, v31
	v_mov_b32_e32 v42, v39
	v_add_u32_e32 v3, 16, v3
	v_pk_fma_f32 v[6:7], v[52:53], v[60:61], v[6:7] op_sel_hi:[0,1,1]
	v_pk_fma_f32 v[8:9], v[52:53], v[62:63], v[8:9] op_sel_hi:[0,1,1]
	v_pk_fma_f32 v[10:11], v[52:53], v[64:65], v[10:11] op_sel_hi:[0,1,1]
	v_pk_fma_f32 v[12:13], v[52:53], v[66:67], v[12:13] op_sel_hi:[0,1,1]
	s_waitcnt lgkmcnt(0)
	v_fmac_f32_e32 v15, v52, v48
	v_pk_fma_f32 v[6:7], v[54:55], v[16:17], v[6:7] op_sel_hi:[0,1,1]
	v_pk_fma_f32 v[8:9], v[54:55], v[24:25], v[8:9] op_sel_hi:[0,1,1]
	v_pk_fma_f32 v[10:11], v[54:55], v[32:33], v[10:11] op_sel_hi:[0,1,1]
	v_pk_fma_f32 v[12:13], v[54:55], v[40:41], v[12:13] op_sel_hi:[0,1,1]
	v_fmac_f32_e32 v15, v54, v49
	v_pk_fma_f32 v[6:7], v[56:57], v[20:21], v[6:7] op_sel_hi:[0,1,1]
	v_pk_fma_f32 v[8:9], v[56:57], v[28:29], v[8:9] op_sel_hi:[0,1,1]
	v_pk_fma_f32 v[10:11], v[56:57], v[36:37], v[10:11] op_sel_hi:[0,1,1]
	v_pk_fma_f32 v[12:13], v[56:57], v[44:45], v[12:13] op_sel_hi:[0,1,1]
	v_fmac_f32_e32 v15, v56, v50
	v_pk_fma_f32 v[6:7], v[58:59], v[18:19], v[6:7] op_sel_hi:[0,1,1]
	v_pk_fma_f32 v[8:9], v[58:59], v[26:27], v[8:9] op_sel_hi:[0,1,1]
	v_pk_fma_f32 v[10:11], v[58:59], v[34:35], v[10:11] op_sel_hi:[0,1,1]
	v_pk_fma_f32 v[12:13], v[58:59], v[42:43], v[12:13] op_sel_hi:[0,1,1]
	v_fmac_f32_e32 v15, v58, v51
	s_waitcnt vmcnt(60)
	v_mov_b32_e32 v52, v136
	v_mov_b32_e32 v54, v137
	v_mov_b32_e32 v56, v138
	v_mov_b32_e32 v58, v139
	global_load_dword v136, v[144:145], off
	v_add_co_u32_e32 v144, vcc, s33, v144
	s_nop 1
	v_addc_co_u32_e32 v145, vcc, 0, v145, vcc
	global_load_dword v137, v[144:145], off
	v_add_co_u32_e32 v144, vcc, s33, v144
	s_nop 1
	v_addc_co_u32_e32 v145, vcc, 0, v145, vcc
	global_load_dword v138, v[144:145], off
	v_add_co_u32_e32 v144, vcc, s33, v144
	s_nop 1
	v_addc_co_u32_e32 v145, vcc, 0, v145, vcc
	global_load_dword v139, v[144:145], off
	v_add_co_u32_e32 v144, vcc, s33, v144
	s_nop 1
	v_addc_co_u32_e32 v145, vcc, 0, v145, vcc
	ds_read_b128 v[16:19], v3 offset:4096
	ds_read_b128 v[20:23], v3 offset:8192
	ds_read_b128 v[24:27], v3 offset:12288
	ds_read_b128 v[28:31], v3 offset:16384
	ds_read_b128 v[32:35], v3 offset:20480
	ds_read_b128 v[36:39], v3 offset:24576
	ds_read_b128 v[40:43], v3 offset:28672
	ds_read_b128 v[44:47], v3
	ds_read_b128 v[48:51], v3 offset:32768
	s_waitcnt lgkmcnt(8)
	v_mov_b32_e32 v61, v16
	s_waitcnt lgkmcnt(7)
	v_mov_b32_e32 v62, v20
	s_waitcnt lgkmcnt(6)
	v_mov_b32_e32 v63, v24
	s_waitcnt lgkmcnt(1)
	v_mov_b32_e32 v60, v44
	v_mov_b32_e32 v64, v28
	v_mov_b32_e32 v65, v32
	v_mov_b32_e32 v66, v36
	v_mov_b32_e32 v67, v40
	v_mov_b32_e32 v16, v45
	v_mov_b32_e32 v24, v21
	v_mov_b32_e32 v32, v29
	v_mov_b32_e32 v40, v37
	v_mov_b32_e32 v20, v46
	v_mov_b32_e32 v21, v18
	v_mov_b32_e32 v28, v22
	v_mov_b32_e32 v29, v26
	v_mov_b32_e32 v36, v30
	v_mov_b32_e32 v37, v34
	v_mov_b32_e32 v44, v38
	v_mov_b32_e32 v45, v42
	v_mov_b32_e32 v18, v47
	v_mov_b32_e32 v26, v23
	v_mov_b32_e32 v34, v31
	v_mov_b32_e32 v42, v39
	v_add_u32_e32 v3, 16, v3
	v_pk_fma_f32 v[6:7], v[52:53], v[60:61], v[6:7] op_sel_hi:[0,1,1]
	v_pk_fma_f32 v[8:9], v[52:53], v[62:63], v[8:9] op_sel_hi:[0,1,1]
	v_pk_fma_f32 v[10:11], v[52:53], v[64:65], v[10:11] op_sel_hi:[0,1,1]
	v_pk_fma_f32 v[12:13], v[52:53], v[66:67], v[12:13] op_sel_hi:[0,1,1]
	s_waitcnt lgkmcnt(0)
	v_fmac_f32_e32 v15, v52, v48
	v_pk_fma_f32 v[6:7], v[54:55], v[16:17], v[6:7] op_sel_hi:[0,1,1]
	v_pk_fma_f32 v[8:9], v[54:55], v[24:25], v[8:9] op_sel_hi:[0,1,1]
	v_pk_fma_f32 v[10:11], v[54:55], v[32:33], v[10:11] op_sel_hi:[0,1,1]
	v_pk_fma_f32 v[12:13], v[54:55], v[40:41], v[12:13] op_sel_hi:[0,1,1]
	v_fmac_f32_e32 v15, v54, v49
	v_pk_fma_f32 v[6:7], v[56:57], v[20:21], v[6:7] op_sel_hi:[0,1,1]
	v_pk_fma_f32 v[8:9], v[56:57], v[28:29], v[8:9] op_sel_hi:[0,1,1]
	v_pk_fma_f32 v[10:11], v[56:57], v[36:37], v[10:11] op_sel_hi:[0,1,1]
	v_pk_fma_f32 v[12:13], v[56:57], v[44:45], v[12:13] op_sel_hi:[0,1,1]
	v_fmac_f32_e32 v15, v56, v50
	v_pk_fma_f32 v[6:7], v[58:59], v[18:19], v[6:7] op_sel_hi:[0,1,1]
	v_pk_fma_f32 v[8:9], v[58:59], v[26:27], v[8:9] op_sel_hi:[0,1,1]
	v_pk_fma_f32 v[10:11], v[58:59], v[34:35], v[10:11] op_sel_hi:[0,1,1]
	v_pk_fma_f32 v[12:13], v[58:59], v[42:43], v[12:13] op_sel_hi:[0,1,1]
	v_fmac_f32_e32 v15, v58, v51
	s_waitcnt vmcnt(60)
	v_mov_b32_e32 v52, v140
	v_mov_b32_e32 v54, v141
	v_mov_b32_e32 v56, v142
	v_mov_b32_e32 v58, v143
	global_load_dword v140, v[144:145], off
	v_add_co_u32_e32 v144, vcc, s33, v144
	s_nop 1
	v_addc_co_u32_e32 v145, vcc, 0, v145, vcc
	global_load_dword v141, v[144:145], off
	v_add_co_u32_e32 v144, vcc, s33, v144
	s_nop 1
	v_addc_co_u32_e32 v145, vcc, 0, v145, vcc
	global_load_dword v142, v[144:145], off
	v_add_co_u32_e32 v144, vcc, s33, v144
	s_nop 1
	v_addc_co_u32_e32 v145, vcc, 0, v145, vcc
	global_load_dword v143, v[144:145], off
	v_add_co_u32_e32 v144, vcc, s33, v144
	s_nop 1
	v_addc_co_u32_e32 v145, vcc, 0, v145, vcc
	ds_read_b128 v[16:19], v3 offset:4096
	ds_read_b128 v[20:23], v3 offset:8192
	ds_read_b128 v[24:27], v3 offset:12288
	ds_read_b128 v[28:31], v3 offset:16384
	ds_read_b128 v[32:35], v3 offset:20480
	ds_read_b128 v[36:39], v3 offset:24576
	ds_read_b128 v[40:43], v3 offset:28672
	ds_read_b128 v[44:47], v3
	ds_read_b128 v[48:51], v3 offset:32768
	s_waitcnt lgkmcnt(8)
	v_mov_b32_e32 v61, v16
	s_waitcnt lgkmcnt(7)
	v_mov_b32_e32 v62, v20
	s_waitcnt lgkmcnt(6)
	v_mov_b32_e32 v63, v24
	s_waitcnt lgkmcnt(1)
	v_mov_b32_e32 v60, v44
	v_mov_b32_e32 v64, v28
	v_mov_b32_e32 v65, v32
	v_mov_b32_e32 v66, v36
	v_mov_b32_e32 v67, v40
	v_mov_b32_e32 v16, v45
	v_mov_b32_e32 v24, v21
	v_mov_b32_e32 v32, v29
	v_mov_b32_e32 v40, v37
	v_mov_b32_e32 v20, v46
	v_mov_b32_e32 v21, v18
	v_mov_b32_e32 v28, v22
	v_mov_b32_e32 v29, v26
	v_mov_b32_e32 v36, v30
	v_mov_b32_e32 v37, v34
	v_mov_b32_e32 v44, v38
	v_mov_b32_e32 v45, v42
	v_mov_b32_e32 v18, v47
	v_mov_b32_e32 v26, v23
	v_mov_b32_e32 v34, v31
	v_mov_b32_e32 v42, v39
	v_add_u32_e32 v3, 16, v3
	v_pk_fma_f32 v[6:7], v[52:53], v[60:61], v[6:7] op_sel_hi:[0,1,1]
	v_pk_fma_f32 v[8:9], v[52:53], v[62:63], v[8:9] op_sel_hi:[0,1,1]
	v_pk_fma_f32 v[10:11], v[52:53], v[64:65], v[10:11] op_sel_hi:[0,1,1]
	v_pk_fma_f32 v[12:13], v[52:53], v[66:67], v[12:13] op_sel_hi:[0,1,1]
	s_waitcnt lgkmcnt(0)
	v_fmac_f32_e32 v15, v52, v48
	v_pk_fma_f32 v[6:7], v[54:55], v[16:17], v[6:7] op_sel_hi:[0,1,1]
	v_pk_fma_f32 v[8:9], v[54:55], v[24:25], v[8:9] op_sel_hi:[0,1,1]
	v_pk_fma_f32 v[10:11], v[54:55], v[32:33], v[10:11] op_sel_hi:[0,1,1]
	v_pk_fma_f32 v[12:13], v[54:55], v[40:41], v[12:13] op_sel_hi:[0,1,1]
	v_fmac_f32_e32 v15, v54, v49
	v_pk_fma_f32 v[6:7], v[56:57], v[20:21], v[6:7] op_sel_hi:[0,1,1]
	v_pk_fma_f32 v[8:9], v[56:57], v[28:29], v[8:9] op_sel_hi:[0,1,1]
	v_pk_fma_f32 v[10:11], v[56:57], v[36:37], v[10:11] op_sel_hi:[0,1,1]
	v_pk_fma_f32 v[12:13], v[56:57], v[44:45], v[12:13] op_sel_hi:[0,1,1]
	v_fmac_f32_e32 v15, v56, v50
	v_pk_fma_f32 v[6:7], v[58:59], v[18:19], v[6:7] op_sel_hi:[0,1,1]
	v_pk_fma_f32 v[8:9], v[58:59], v[26:27], v[8:9] op_sel_hi:[0,1,1]
	v_pk_fma_f32 v[10:11], v[58:59], v[34:35], v[10:11] op_sel_hi:[0,1,1]
	v_pk_fma_f32 v[12:13], v[58:59], v[42:43], v[12:13] op_sel_hi:[0,1,1]
	v_fmac_f32_e32 v15, v58, v51
	s_waitcnt vmcnt(60)
	v_mov_b32_e32 v52, v80
	v_mov_b32_e32 v54, v81
	v_mov_b32_e32 v56, v82
	v_mov_b32_e32 v58, v83
	ds_read_b128 v[16:19], v3 offset:4096
	ds_read_b128 v[20:23], v3 offset:8192
	ds_read_b128 v[24:27], v3 offset:12288
	ds_read_b128 v[28:31], v3 offset:16384
	ds_read_b128 v[32:35], v3 offset:20480
	ds_read_b128 v[36:39], v3 offset:24576
	ds_read_b128 v[40:43], v3 offset:28672
	ds_read_b128 v[44:47], v3
	ds_read_b128 v[48:51], v3 offset:32768
	s_waitcnt lgkmcnt(8)
	v_mov_b32_e32 v61, v16
	s_waitcnt lgkmcnt(7)
	v_mov_b32_e32 v62, v20
	s_waitcnt lgkmcnt(6)
	v_mov_b32_e32 v63, v24
	s_waitcnt lgkmcnt(1)
	v_mov_b32_e32 v60, v44
	v_mov_b32_e32 v64, v28
	v_mov_b32_e32 v65, v32
	v_mov_b32_e32 v66, v36
	v_mov_b32_e32 v67, v40
	v_mov_b32_e32 v16, v45
	v_mov_b32_e32 v24, v21
	v_mov_b32_e32 v32, v29
	v_mov_b32_e32 v40, v37
	v_mov_b32_e32 v20, v46
	v_mov_b32_e32 v21, v18
	v_mov_b32_e32 v28, v22
	v_mov_b32_e32 v29, v26
	v_mov_b32_e32 v36, v30
	v_mov_b32_e32 v37, v34
	v_mov_b32_e32 v44, v38
	v_mov_b32_e32 v45, v42
	v_mov_b32_e32 v18, v47
	v_mov_b32_e32 v26, v23
	v_mov_b32_e32 v34, v31
	v_mov_b32_e32 v42, v39
	v_add_u32_e32 v3, 16, v3
	v_pk_fma_f32 v[6:7], v[52:53], v[60:61], v[6:7] op_sel_hi:[0,1,1]
	v_pk_fma_f32 v[8:9], v[52:53], v[62:63], v[8:9] op_sel_hi:[0,1,1]
	v_pk_fma_f32 v[10:11], v[52:53], v[64:65], v[10:11] op_sel_hi:[0,1,1]
	v_pk_fma_f32 v[12:13], v[52:53], v[66:67], v[12:13] op_sel_hi:[0,1,1]
	s_waitcnt lgkmcnt(0)
	v_fmac_f32_e32 v15, v52, v48
	v_pk_fma_f32 v[6:7], v[54:55], v[16:17], v[6:7] op_sel_hi:[0,1,1]
	v_pk_fma_f32 v[8:9], v[54:55], v[24:25], v[8:9] op_sel_hi:[0,1,1]
	v_pk_fma_f32 v[10:11], v[54:55], v[32:33], v[10:11] op_sel_hi:[0,1,1]
	v_pk_fma_f32 v[12:13], v[54:55], v[40:41], v[12:13] op_sel_hi:[0,1,1]
	v_fmac_f32_e32 v15, v54, v49
	v_pk_fma_f32 v[6:7], v[56:57], v[20:21], v[6:7] op_sel_hi:[0,1,1]
	v_pk_fma_f32 v[8:9], v[56:57], v[28:29], v[8:9] op_sel_hi:[0,1,1]
	v_pk_fma_f32 v[10:11], v[56:57], v[36:37], v[10:11] op_sel_hi:[0,1,1]
	v_pk_fma_f32 v[12:13], v[56:57], v[44:45], v[12:13] op_sel_hi:[0,1,1]
	v_fmac_f32_e32 v15, v56, v50
	v_pk_fma_f32 v[6:7], v[58:59], v[18:19], v[6:7] op_sel_hi:[0,1,1]
	v_pk_fma_f32 v[8:9], v[58:59], v[26:27], v[8:9] op_sel_hi:[0,1,1]
	v_pk_fma_f32 v[10:11], v[58:59], v[34:35], v[10:11] op_sel_hi:[0,1,1]
	v_pk_fma_f32 v[12:13], v[58:59], v[42:43], v[12:13] op_sel_hi:[0,1,1]
	v_fmac_f32_e32 v15, v58, v51
	s_waitcnt vmcnt(56)
	v_mov_b32_e32 v52, v84
	v_mov_b32_e32 v54, v85
	v_mov_b32_e32 v56, v86
	v_mov_b32_e32 v58, v87
	ds_read_b128 v[16:19], v3 offset:4096
	ds_read_b128 v[20:23], v3 offset:8192
	ds_read_b128 v[24:27], v3 offset:12288
	ds_read_b128 v[28:31], v3 offset:16384
	ds_read_b128 v[32:35], v3 offset:20480
	ds_read_b128 v[36:39], v3 offset:24576
	ds_read_b128 v[40:43], v3 offset:28672
	ds_read_b128 v[44:47], v3
	ds_read_b128 v[48:51], v3 offset:32768
	s_waitcnt lgkmcnt(8)
	v_mov_b32_e32 v61, v16
	s_waitcnt lgkmcnt(7)
	v_mov_b32_e32 v62, v20
	s_waitcnt lgkmcnt(6)
	v_mov_b32_e32 v63, v24
	s_waitcnt lgkmcnt(1)
	v_mov_b32_e32 v60, v44
	v_mov_b32_e32 v64, v28
	v_mov_b32_e32 v65, v32
	v_mov_b32_e32 v66, v36
	v_mov_b32_e32 v67, v40
	v_mov_b32_e32 v16, v45
	v_mov_b32_e32 v24, v21
	v_mov_b32_e32 v32, v29
	v_mov_b32_e32 v40, v37
	v_mov_b32_e32 v20, v46
	v_mov_b32_e32 v21, v18
	v_mov_b32_e32 v28, v22
	v_mov_b32_e32 v29, v26
	v_mov_b32_e32 v36, v30
	v_mov_b32_e32 v37, v34
	v_mov_b32_e32 v44, v38
	v_mov_b32_e32 v45, v42
	v_mov_b32_e32 v18, v47
	v_mov_b32_e32 v26, v23
	v_mov_b32_e32 v34, v31
	v_mov_b32_e32 v42, v39
	v_add_u32_e32 v3, 16, v3
	v_pk_fma_f32 v[6:7], v[52:53], v[60:61], v[6:7] op_sel_hi:[0,1,1]
	v_pk_fma_f32 v[8:9], v[52:53], v[62:63], v[8:9] op_sel_hi:[0,1,1]
	v_pk_fma_f32 v[10:11], v[52:53], v[64:65], v[10:11] op_sel_hi:[0,1,1]
	v_pk_fma_f32 v[12:13], v[52:53], v[66:67], v[12:13] op_sel_hi:[0,1,1]
	s_waitcnt lgkmcnt(0)
	v_fmac_f32_e32 v15, v52, v48
	v_pk_fma_f32 v[6:7], v[54:55], v[16:17], v[6:7] op_sel_hi:[0,1,1]
	v_pk_fma_f32 v[8:9], v[54:55], v[24:25], v[8:9] op_sel_hi:[0,1,1]
	v_pk_fma_f32 v[10:11], v[54:55], v[32:33], v[10:11] op_sel_hi:[0,1,1]
	v_pk_fma_f32 v[12:13], v[54:55], v[40:41], v[12:13] op_sel_hi:[0,1,1]
	v_fmac_f32_e32 v15, v54, v49
	v_pk_fma_f32 v[6:7], v[56:57], v[20:21], v[6:7] op_sel_hi:[0,1,1]
	v_pk_fma_f32 v[8:9], v[56:57], v[28:29], v[8:9] op_sel_hi:[0,1,1]
	v_pk_fma_f32 v[10:11], v[56:57], v[36:37], v[10:11] op_sel_hi:[0,1,1]
	v_pk_fma_f32 v[12:13], v[56:57], v[44:45], v[12:13] op_sel_hi:[0,1,1]
	v_fmac_f32_e32 v15, v56, v50
	v_pk_fma_f32 v[6:7], v[58:59], v[18:19], v[6:7] op_sel_hi:[0,1,1]
	v_pk_fma_f32 v[8:9], v[58:59], v[26:27], v[8:9] op_sel_hi:[0,1,1]
	v_pk_fma_f32 v[10:11], v[58:59], v[34:35], v[10:11] op_sel_hi:[0,1,1]
	v_pk_fma_f32 v[12:13], v[58:59], v[42:43], v[12:13] op_sel_hi:[0,1,1]
	v_fmac_f32_e32 v15, v58, v51
	s_waitcnt vmcnt(52)
	v_mov_b32_e32 v52, v88
	v_mov_b32_e32 v54, v89
	v_mov_b32_e32 v56, v90
	v_mov_b32_e32 v58, v91
	ds_read_b128 v[16:19], v3 offset:4096
	ds_read_b128 v[20:23], v3 offset:8192
	ds_read_b128 v[24:27], v3 offset:12288
	ds_read_b128 v[28:31], v3 offset:16384
	ds_read_b128 v[32:35], v3 offset:20480
	ds_read_b128 v[36:39], v3 offset:24576
	ds_read_b128 v[40:43], v3 offset:28672
	ds_read_b128 v[44:47], v3
	ds_read_b128 v[48:51], v3 offset:32768
	s_waitcnt lgkmcnt(8)
	v_mov_b32_e32 v61, v16
	s_waitcnt lgkmcnt(7)
	v_mov_b32_e32 v62, v20
	s_waitcnt lgkmcnt(6)
	v_mov_b32_e32 v63, v24
	s_waitcnt lgkmcnt(1)
	v_mov_b32_e32 v60, v44
	v_mov_b32_e32 v64, v28
	v_mov_b32_e32 v65, v32
	v_mov_b32_e32 v66, v36
	v_mov_b32_e32 v67, v40
	v_mov_b32_e32 v16, v45
	v_mov_b32_e32 v24, v21
	v_mov_b32_e32 v32, v29
	v_mov_b32_e32 v40, v37
	v_mov_b32_e32 v20, v46
	v_mov_b32_e32 v21, v18
	v_mov_b32_e32 v28, v22
	v_mov_b32_e32 v29, v26
	v_mov_b32_e32 v36, v30
	v_mov_b32_e32 v37, v34
	v_mov_b32_e32 v44, v38
	v_mov_b32_e32 v45, v42
	v_mov_b32_e32 v18, v47
	v_mov_b32_e32 v26, v23
	v_mov_b32_e32 v34, v31
	v_mov_b32_e32 v42, v39
	v_add_u32_e32 v3, 16, v3
	v_pk_fma_f32 v[6:7], v[52:53], v[60:61], v[6:7] op_sel_hi:[0,1,1]
	v_pk_fma_f32 v[8:9], v[52:53], v[62:63], v[8:9] op_sel_hi:[0,1,1]
	v_pk_fma_f32 v[10:11], v[52:53], v[64:65], v[10:11] op_sel_hi:[0,1,1]
	v_pk_fma_f32 v[12:13], v[52:53], v[66:67], v[12:13] op_sel_hi:[0,1,1]
	s_waitcnt lgkmcnt(0)
	v_fmac_f32_e32 v15, v52, v48
	v_pk_fma_f32 v[6:7], v[54:55], v[16:17], v[6:7] op_sel_hi:[0,1,1]
	v_pk_fma_f32 v[8:9], v[54:55], v[24:25], v[8:9] op_sel_hi:[0,1,1]
	v_pk_fma_f32 v[10:11], v[54:55], v[32:33], v[10:11] op_sel_hi:[0,1,1]
	v_pk_fma_f32 v[12:13], v[54:55], v[40:41], v[12:13] op_sel_hi:[0,1,1]
	v_fmac_f32_e32 v15, v54, v49
	v_pk_fma_f32 v[6:7], v[56:57], v[20:21], v[6:7] op_sel_hi:[0,1,1]
	v_pk_fma_f32 v[8:9], v[56:57], v[28:29], v[8:9] op_sel_hi:[0,1,1]
	v_pk_fma_f32 v[10:11], v[56:57], v[36:37], v[10:11] op_sel_hi:[0,1,1]
	v_pk_fma_f32 v[12:13], v[56:57], v[44:45], v[12:13] op_sel_hi:[0,1,1]
	v_fmac_f32_e32 v15, v56, v50
	v_pk_fma_f32 v[6:7], v[58:59], v[18:19], v[6:7] op_sel_hi:[0,1,1]
	v_pk_fma_f32 v[8:9], v[58:59], v[26:27], v[8:9] op_sel_hi:[0,1,1]
	v_pk_fma_f32 v[10:11], v[58:59], v[34:35], v[10:11] op_sel_hi:[0,1,1]
	v_pk_fma_f32 v[12:13], v[58:59], v[42:43], v[12:13] op_sel_hi:[0,1,1]
	v_fmac_f32_e32 v15, v58, v51
	s_waitcnt vmcnt(48)
	v_mov_b32_e32 v52, v92
	v_mov_b32_e32 v54, v93
	v_mov_b32_e32 v56, v94
	v_mov_b32_e32 v58, v95
	ds_read_b128 v[16:19], v3 offset:4096
	ds_read_b128 v[20:23], v3 offset:8192
	ds_read_b128 v[24:27], v3 offset:12288
	ds_read_b128 v[28:31], v3 offset:16384
	ds_read_b128 v[32:35], v3 offset:20480
	ds_read_b128 v[36:39], v3 offset:24576
	ds_read_b128 v[40:43], v3 offset:28672
	ds_read_b128 v[44:47], v3
	ds_read_b128 v[48:51], v3 offset:32768
	s_waitcnt lgkmcnt(8)
	v_mov_b32_e32 v61, v16
	s_waitcnt lgkmcnt(7)
	v_mov_b32_e32 v62, v20
	s_waitcnt lgkmcnt(6)
	v_mov_b32_e32 v63, v24
	s_waitcnt lgkmcnt(1)
	v_mov_b32_e32 v60, v44
	v_mov_b32_e32 v64, v28
	v_mov_b32_e32 v65, v32
	v_mov_b32_e32 v66, v36
	v_mov_b32_e32 v67, v40
	v_mov_b32_e32 v16, v45
	v_mov_b32_e32 v24, v21
	v_mov_b32_e32 v32, v29
	v_mov_b32_e32 v40, v37
	v_mov_b32_e32 v20, v46
	v_mov_b32_e32 v21, v18
	v_mov_b32_e32 v28, v22
	v_mov_b32_e32 v29, v26
	v_mov_b32_e32 v36, v30
	v_mov_b32_e32 v37, v34
	v_mov_b32_e32 v44, v38
	v_mov_b32_e32 v45, v42
	v_mov_b32_e32 v18, v47
	v_mov_b32_e32 v26, v23
	v_mov_b32_e32 v34, v31
	v_mov_b32_e32 v42, v39
	v_add_u32_e32 v3, 16, v3
	v_pk_fma_f32 v[6:7], v[52:53], v[60:61], v[6:7] op_sel_hi:[0,1,1]
	v_pk_fma_f32 v[8:9], v[52:53], v[62:63], v[8:9] op_sel_hi:[0,1,1]
	v_pk_fma_f32 v[10:11], v[52:53], v[64:65], v[10:11] op_sel_hi:[0,1,1]
	v_pk_fma_f32 v[12:13], v[52:53], v[66:67], v[12:13] op_sel_hi:[0,1,1]
	s_waitcnt lgkmcnt(0)
	v_fmac_f32_e32 v15, v52, v48
	v_pk_fma_f32 v[6:7], v[54:55], v[16:17], v[6:7] op_sel_hi:[0,1,1]
	v_pk_fma_f32 v[8:9], v[54:55], v[24:25], v[8:9] op_sel_hi:[0,1,1]
	v_pk_fma_f32 v[10:11], v[54:55], v[32:33], v[10:11] op_sel_hi:[0,1,1]
	v_pk_fma_f32 v[12:13], v[54:55], v[40:41], v[12:13] op_sel_hi:[0,1,1]
	v_fmac_f32_e32 v15, v54, v49
	v_pk_fma_f32 v[6:7], v[56:57], v[20:21], v[6:7] op_sel_hi:[0,1,1]
	v_pk_fma_f32 v[8:9], v[56:57], v[28:29], v[8:9] op_sel_hi:[0,1,1]
	v_pk_fma_f32 v[10:11], v[56:57], v[36:37], v[10:11] op_sel_hi:[0,1,1]
	v_pk_fma_f32 v[12:13], v[56:57], v[44:45], v[12:13] op_sel_hi:[0,1,1]
	v_fmac_f32_e32 v15, v56, v50
	v_pk_fma_f32 v[6:7], v[58:59], v[18:19], v[6:7] op_sel_hi:[0,1,1]
	v_pk_fma_f32 v[8:9], v[58:59], v[26:27], v[8:9] op_sel_hi:[0,1,1]
	v_pk_fma_f32 v[10:11], v[58:59], v[34:35], v[10:11] op_sel_hi:[0,1,1]
	v_pk_fma_f32 v[12:13], v[58:59], v[42:43], v[12:13] op_sel_hi:[0,1,1]
	v_fmac_f32_e32 v15, v58, v51
	s_waitcnt vmcnt(44)
	v_mov_b32_e32 v52, v96
	v_mov_b32_e32 v54, v97
	v_mov_b32_e32 v56, v98
	v_mov_b32_e32 v58, v99
	ds_read_b128 v[16:19], v3 offset:4096
	ds_read_b128 v[20:23], v3 offset:8192
	ds_read_b128 v[24:27], v3 offset:12288
	ds_read_b128 v[28:31], v3 offset:16384
	ds_read_b128 v[32:35], v3 offset:20480
	ds_read_b128 v[36:39], v3 offset:24576
	ds_read_b128 v[40:43], v3 offset:28672
	ds_read_b128 v[44:47], v3
	ds_read_b128 v[48:51], v3 offset:32768
	s_waitcnt lgkmcnt(8)
	v_mov_b32_e32 v61, v16
	s_waitcnt lgkmcnt(7)
	v_mov_b32_e32 v62, v20
	s_waitcnt lgkmcnt(6)
	v_mov_b32_e32 v63, v24
	s_waitcnt lgkmcnt(1)
	v_mov_b32_e32 v60, v44
	v_mov_b32_e32 v64, v28
	v_mov_b32_e32 v65, v32
	v_mov_b32_e32 v66, v36
	v_mov_b32_e32 v67, v40
	v_mov_b32_e32 v16, v45
	v_mov_b32_e32 v24, v21
	v_mov_b32_e32 v32, v29
	v_mov_b32_e32 v40, v37
	v_mov_b32_e32 v20, v46
	v_mov_b32_e32 v21, v18
	v_mov_b32_e32 v28, v22
	v_mov_b32_e32 v29, v26
	v_mov_b32_e32 v36, v30
	v_mov_b32_e32 v37, v34
	v_mov_b32_e32 v44, v38
	v_mov_b32_e32 v45, v42
	v_mov_b32_e32 v18, v47
	v_mov_b32_e32 v26, v23
	v_mov_b32_e32 v34, v31
	v_mov_b32_e32 v42, v39
	v_add_u32_e32 v3, 16, v3
	v_pk_fma_f32 v[6:7], v[52:53], v[60:61], v[6:7] op_sel_hi:[0,1,1]
	v_pk_fma_f32 v[8:9], v[52:53], v[62:63], v[8:9] op_sel_hi:[0,1,1]
	v_pk_fma_f32 v[10:11], v[52:53], v[64:65], v[10:11] op_sel_hi:[0,1,1]
	v_pk_fma_f32 v[12:13], v[52:53], v[66:67], v[12:13] op_sel_hi:[0,1,1]
	s_waitcnt lgkmcnt(0)
	v_fmac_f32_e32 v15, v52, v48
	v_pk_fma_f32 v[6:7], v[54:55], v[16:17], v[6:7] op_sel_hi:[0,1,1]
	v_pk_fma_f32 v[8:9], v[54:55], v[24:25], v[8:9] op_sel_hi:[0,1,1]
	v_pk_fma_f32 v[10:11], v[54:55], v[32:33], v[10:11] op_sel_hi:[0,1,1]
	v_pk_fma_f32 v[12:13], v[54:55], v[40:41], v[12:13] op_sel_hi:[0,1,1]
	v_fmac_f32_e32 v15, v54, v49
	v_pk_fma_f32 v[6:7], v[56:57], v[20:21], v[6:7] op_sel_hi:[0,1,1]
	v_pk_fma_f32 v[8:9], v[56:57], v[28:29], v[8:9] op_sel_hi:[0,1,1]
	v_pk_fma_f32 v[10:11], v[56:57], v[36:37], v[10:11] op_sel_hi:[0,1,1]
	v_pk_fma_f32 v[12:13], v[56:57], v[44:45], v[12:13] op_sel_hi:[0,1,1]
	v_fmac_f32_e32 v15, v56, v50
	v_pk_fma_f32 v[6:7], v[58:59], v[18:19], v[6:7] op_sel_hi:[0,1,1]
	v_pk_fma_f32 v[8:9], v[58:59], v[26:27], v[8:9] op_sel_hi:[0,1,1]
	v_pk_fma_f32 v[10:11], v[58:59], v[34:35], v[10:11] op_sel_hi:[0,1,1]
	v_pk_fma_f32 v[12:13], v[58:59], v[42:43], v[12:13] op_sel_hi:[0,1,1]
	v_fmac_f32_e32 v15, v58, v51
	s_waitcnt vmcnt(40)
	v_mov_b32_e32 v52, v100
	v_mov_b32_e32 v54, v101
	v_mov_b32_e32 v56, v102
	v_mov_b32_e32 v58, v103
	ds_read_b128 v[16:19], v3 offset:4096
	ds_read_b128 v[20:23], v3 offset:8192
	ds_read_b128 v[24:27], v3 offset:12288
	ds_read_b128 v[28:31], v3 offset:16384
	ds_read_b128 v[32:35], v3 offset:20480
	ds_read_b128 v[36:39], v3 offset:24576
	ds_read_b128 v[40:43], v3 offset:28672
	ds_read_b128 v[44:47], v3
	ds_read_b128 v[48:51], v3 offset:32768
	s_waitcnt lgkmcnt(8)
	v_mov_b32_e32 v61, v16
	s_waitcnt lgkmcnt(7)
	v_mov_b32_e32 v62, v20
	s_waitcnt lgkmcnt(6)
	v_mov_b32_e32 v63, v24
	s_waitcnt lgkmcnt(1)
	v_mov_b32_e32 v60, v44
	v_mov_b32_e32 v64, v28
	v_mov_b32_e32 v65, v32
	v_mov_b32_e32 v66, v36
	v_mov_b32_e32 v67, v40
	v_mov_b32_e32 v16, v45
	v_mov_b32_e32 v24, v21
	v_mov_b32_e32 v32, v29
	v_mov_b32_e32 v40, v37
	v_mov_b32_e32 v20, v46
	v_mov_b32_e32 v21, v18
	v_mov_b32_e32 v28, v22
	v_mov_b32_e32 v29, v26
	v_mov_b32_e32 v36, v30
	v_mov_b32_e32 v37, v34
	v_mov_b32_e32 v44, v38
	v_mov_b32_e32 v45, v42
	v_mov_b32_e32 v18, v47
	v_mov_b32_e32 v26, v23
	v_mov_b32_e32 v34, v31
	v_mov_b32_e32 v42, v39
	v_add_u32_e32 v3, 16, v3
	v_pk_fma_f32 v[6:7], v[52:53], v[60:61], v[6:7] op_sel_hi:[0,1,1]
	v_pk_fma_f32 v[8:9], v[52:53], v[62:63], v[8:9] op_sel_hi:[0,1,1]
	v_pk_fma_f32 v[10:11], v[52:53], v[64:65], v[10:11] op_sel_hi:[0,1,1]
	v_pk_fma_f32 v[12:13], v[52:53], v[66:67], v[12:13] op_sel_hi:[0,1,1]
	s_waitcnt lgkmcnt(0)
	v_fmac_f32_e32 v15, v52, v48
	v_pk_fma_f32 v[6:7], v[54:55], v[16:17], v[6:7] op_sel_hi:[0,1,1]
	v_pk_fma_f32 v[8:9], v[54:55], v[24:25], v[8:9] op_sel_hi:[0,1,1]
	v_pk_fma_f32 v[10:11], v[54:55], v[32:33], v[10:11] op_sel_hi:[0,1,1]
	v_pk_fma_f32 v[12:13], v[54:55], v[40:41], v[12:13] op_sel_hi:[0,1,1]
	v_fmac_f32_e32 v15, v54, v49
	v_pk_fma_f32 v[6:7], v[56:57], v[20:21], v[6:7] op_sel_hi:[0,1,1]
	v_pk_fma_f32 v[8:9], v[56:57], v[28:29], v[8:9] op_sel_hi:[0,1,1]
	v_pk_fma_f32 v[10:11], v[56:57], v[36:37], v[10:11] op_sel_hi:[0,1,1]
	v_pk_fma_f32 v[12:13], v[56:57], v[44:45], v[12:13] op_sel_hi:[0,1,1]
	v_fmac_f32_e32 v15, v56, v50
	v_pk_fma_f32 v[6:7], v[58:59], v[18:19], v[6:7] op_sel_hi:[0,1,1]
	v_pk_fma_f32 v[8:9], v[58:59], v[26:27], v[8:9] op_sel_hi:[0,1,1]
	v_pk_fma_f32 v[10:11], v[58:59], v[34:35], v[10:11] op_sel_hi:[0,1,1]
	v_pk_fma_f32 v[12:13], v[58:59], v[42:43], v[12:13] op_sel_hi:[0,1,1]
	v_fmac_f32_e32 v15, v58, v51
	s_waitcnt vmcnt(36)
	v_mov_b32_e32 v52, v104
	v_mov_b32_e32 v54, v105
	v_mov_b32_e32 v56, v106
	v_mov_b32_e32 v58, v107
	ds_read_b128 v[16:19], v3 offset:4096
	ds_read_b128 v[20:23], v3 offset:8192
	ds_read_b128 v[24:27], v3 offset:12288
	ds_read_b128 v[28:31], v3 offset:16384
	ds_read_b128 v[32:35], v3 offset:20480
	ds_read_b128 v[36:39], v3 offset:24576
	ds_read_b128 v[40:43], v3 offset:28672
	ds_read_b128 v[44:47], v3
	ds_read_b128 v[48:51], v3 offset:32768
	s_waitcnt lgkmcnt(8)
	v_mov_b32_e32 v61, v16
	s_waitcnt lgkmcnt(7)
	v_mov_b32_e32 v62, v20
	s_waitcnt lgkmcnt(6)
	v_mov_b32_e32 v63, v24
	s_waitcnt lgkmcnt(1)
	v_mov_b32_e32 v60, v44
	v_mov_b32_e32 v64, v28
	v_mov_b32_e32 v65, v32
	v_mov_b32_e32 v66, v36
	v_mov_b32_e32 v67, v40
	v_mov_b32_e32 v16, v45
	v_mov_b32_e32 v24, v21
	v_mov_b32_e32 v32, v29
	v_mov_b32_e32 v40, v37
	v_mov_b32_e32 v20, v46
	v_mov_b32_e32 v21, v18
	v_mov_b32_e32 v28, v22
	v_mov_b32_e32 v29, v26
	v_mov_b32_e32 v36, v30
	v_mov_b32_e32 v37, v34
	v_mov_b32_e32 v44, v38
	v_mov_b32_e32 v45, v42
	v_mov_b32_e32 v18, v47
	v_mov_b32_e32 v26, v23
	v_mov_b32_e32 v34, v31
	v_mov_b32_e32 v42, v39
	v_add_u32_e32 v3, 16, v3
	v_pk_fma_f32 v[6:7], v[52:53], v[60:61], v[6:7] op_sel_hi:[0,1,1]
	v_pk_fma_f32 v[8:9], v[52:53], v[62:63], v[8:9] op_sel_hi:[0,1,1]
	v_pk_fma_f32 v[10:11], v[52:53], v[64:65], v[10:11] op_sel_hi:[0,1,1]
	v_pk_fma_f32 v[12:13], v[52:53], v[66:67], v[12:13] op_sel_hi:[0,1,1]
	s_waitcnt lgkmcnt(0)
	v_fmac_f32_e32 v15, v52, v48
	v_pk_fma_f32 v[6:7], v[54:55], v[16:17], v[6:7] op_sel_hi:[0,1,1]
	v_pk_fma_f32 v[8:9], v[54:55], v[24:25], v[8:9] op_sel_hi:[0,1,1]
	v_pk_fma_f32 v[10:11], v[54:55], v[32:33], v[10:11] op_sel_hi:[0,1,1]
	v_pk_fma_f32 v[12:13], v[54:55], v[40:41], v[12:13] op_sel_hi:[0,1,1]
	v_fmac_f32_e32 v15, v54, v49
	v_pk_fma_f32 v[6:7], v[56:57], v[20:21], v[6:7] op_sel_hi:[0,1,1]
	v_pk_fma_f32 v[8:9], v[56:57], v[28:29], v[8:9] op_sel_hi:[0,1,1]
	v_pk_fma_f32 v[10:11], v[56:57], v[36:37], v[10:11] op_sel_hi:[0,1,1]
	v_pk_fma_f32 v[12:13], v[56:57], v[44:45], v[12:13] op_sel_hi:[0,1,1]
	v_fmac_f32_e32 v15, v56, v50
	v_pk_fma_f32 v[6:7], v[58:59], v[18:19], v[6:7] op_sel_hi:[0,1,1]
	v_pk_fma_f32 v[8:9], v[58:59], v[26:27], v[8:9] op_sel_hi:[0,1,1]
	v_pk_fma_f32 v[10:11], v[58:59], v[34:35], v[10:11] op_sel_hi:[0,1,1]
	v_pk_fma_f32 v[12:13], v[58:59], v[42:43], v[12:13] op_sel_hi:[0,1,1]
	v_fmac_f32_e32 v15, v58, v51
	s_waitcnt vmcnt(32)
	v_mov_b32_e32 v52, v108
	v_mov_b32_e32 v54, v109
	v_mov_b32_e32 v56, v110
	v_mov_b32_e32 v58, v111
	ds_read_b128 v[16:19], v3 offset:4096
	ds_read_b128 v[20:23], v3 offset:8192
	ds_read_b128 v[24:27], v3 offset:12288
	ds_read_b128 v[28:31], v3 offset:16384
	ds_read_b128 v[32:35], v3 offset:20480
	ds_read_b128 v[36:39], v3 offset:24576
	ds_read_b128 v[40:43], v3 offset:28672
	ds_read_b128 v[44:47], v3
	ds_read_b128 v[48:51], v3 offset:32768
	s_waitcnt lgkmcnt(8)
	v_mov_b32_e32 v61, v16
	s_waitcnt lgkmcnt(7)
	v_mov_b32_e32 v62, v20
	s_waitcnt lgkmcnt(6)
	v_mov_b32_e32 v63, v24
	s_waitcnt lgkmcnt(1)
	v_mov_b32_e32 v60, v44
	v_mov_b32_e32 v64, v28
	v_mov_b32_e32 v65, v32
	v_mov_b32_e32 v66, v36
	v_mov_b32_e32 v67, v40
	v_mov_b32_e32 v16, v45
	v_mov_b32_e32 v24, v21
	v_mov_b32_e32 v32, v29
	v_mov_b32_e32 v40, v37
	v_mov_b32_e32 v20, v46
	v_mov_b32_e32 v21, v18
	v_mov_b32_e32 v28, v22
	v_mov_b32_e32 v29, v26
	v_mov_b32_e32 v36, v30
	v_mov_b32_e32 v37, v34
	v_mov_b32_e32 v44, v38
	v_mov_b32_e32 v45, v42
	v_mov_b32_e32 v18, v47
	v_mov_b32_e32 v26, v23
	v_mov_b32_e32 v34, v31
	v_mov_b32_e32 v42, v39
	v_add_u32_e32 v3, 16, v3
	v_pk_fma_f32 v[6:7], v[52:53], v[60:61], v[6:7] op_sel_hi:[0,1,1]
	v_pk_fma_f32 v[8:9], v[52:53], v[62:63], v[8:9] op_sel_hi:[0,1,1]
	v_pk_fma_f32 v[10:11], v[52:53], v[64:65], v[10:11] op_sel_hi:[0,1,1]
	v_pk_fma_f32 v[12:13], v[52:53], v[66:67], v[12:13] op_sel_hi:[0,1,1]
	s_waitcnt lgkmcnt(0)
	v_fmac_f32_e32 v15, v52, v48
	v_pk_fma_f32 v[6:7], v[54:55], v[16:17], v[6:7] op_sel_hi:[0,1,1]
	v_pk_fma_f32 v[8:9], v[54:55], v[24:25], v[8:9] op_sel_hi:[0,1,1]
	v_pk_fma_f32 v[10:11], v[54:55], v[32:33], v[10:11] op_sel_hi:[0,1,1]
	v_pk_fma_f32 v[12:13], v[54:55], v[40:41], v[12:13] op_sel_hi:[0,1,1]
	v_fmac_f32_e32 v15, v54, v49
	v_pk_fma_f32 v[6:7], v[56:57], v[20:21], v[6:7] op_sel_hi:[0,1,1]
	v_pk_fma_f32 v[8:9], v[56:57], v[28:29], v[8:9] op_sel_hi:[0,1,1]
	v_pk_fma_f32 v[10:11], v[56:57], v[36:37], v[10:11] op_sel_hi:[0,1,1]
	v_pk_fma_f32 v[12:13], v[56:57], v[44:45], v[12:13] op_sel_hi:[0,1,1]
	v_fmac_f32_e32 v15, v56, v50
	v_pk_fma_f32 v[6:7], v[58:59], v[18:19], v[6:7] op_sel_hi:[0,1,1]
	v_pk_fma_f32 v[8:9], v[58:59], v[26:27], v[8:9] op_sel_hi:[0,1,1]
	v_pk_fma_f32 v[10:11], v[58:59], v[34:35], v[10:11] op_sel_hi:[0,1,1]
	v_pk_fma_f32 v[12:13], v[58:59], v[42:43], v[12:13] op_sel_hi:[0,1,1]
	v_fmac_f32_e32 v15, v58, v51
	s_waitcnt vmcnt(28)
	v_mov_b32_e32 v52, v112
	v_mov_b32_e32 v54, v113
	v_mov_b32_e32 v56, v114
	v_mov_b32_e32 v58, v115
	ds_read_b128 v[16:19], v3 offset:4096
	ds_read_b128 v[20:23], v3 offset:8192
	ds_read_b128 v[24:27], v3 offset:12288
	ds_read_b128 v[28:31], v3 offset:16384
	ds_read_b128 v[32:35], v3 offset:20480
	ds_read_b128 v[36:39], v3 offset:24576
	ds_read_b128 v[40:43], v3 offset:28672
	ds_read_b128 v[44:47], v3
	ds_read_b128 v[48:51], v3 offset:32768
	s_waitcnt lgkmcnt(8)
	v_mov_b32_e32 v61, v16
	s_waitcnt lgkmcnt(7)
	v_mov_b32_e32 v62, v20
	s_waitcnt lgkmcnt(6)
	v_mov_b32_e32 v63, v24
	s_waitcnt lgkmcnt(1)
	v_mov_b32_e32 v60, v44
	v_mov_b32_e32 v64, v28
	v_mov_b32_e32 v65, v32
	v_mov_b32_e32 v66, v36
	v_mov_b32_e32 v67, v40
	v_mov_b32_e32 v16, v45
	v_mov_b32_e32 v24, v21
	v_mov_b32_e32 v32, v29
	v_mov_b32_e32 v40, v37
	v_mov_b32_e32 v20, v46
	v_mov_b32_e32 v21, v18
	v_mov_b32_e32 v28, v22
	v_mov_b32_e32 v29, v26
	v_mov_b32_e32 v36, v30
	v_mov_b32_e32 v37, v34
	v_mov_b32_e32 v44, v38
	v_mov_b32_e32 v45, v42
	v_mov_b32_e32 v18, v47
	v_mov_b32_e32 v26, v23
	v_mov_b32_e32 v34, v31
	v_mov_b32_e32 v42, v39
	v_add_u32_e32 v3, 16, v3
	v_pk_fma_f32 v[6:7], v[52:53], v[60:61], v[6:7] op_sel_hi:[0,1,1]
	v_pk_fma_f32 v[8:9], v[52:53], v[62:63], v[8:9] op_sel_hi:[0,1,1]
	v_pk_fma_f32 v[10:11], v[52:53], v[64:65], v[10:11] op_sel_hi:[0,1,1]
	v_pk_fma_f32 v[12:13], v[52:53], v[66:67], v[12:13] op_sel_hi:[0,1,1]
	s_waitcnt lgkmcnt(0)
	v_fmac_f32_e32 v15, v52, v48
	v_pk_fma_f32 v[6:7], v[54:55], v[16:17], v[6:7] op_sel_hi:[0,1,1]
	v_pk_fma_f32 v[8:9], v[54:55], v[24:25], v[8:9] op_sel_hi:[0,1,1]
	v_pk_fma_f32 v[10:11], v[54:55], v[32:33], v[10:11] op_sel_hi:[0,1,1]
	v_pk_fma_f32 v[12:13], v[54:55], v[40:41], v[12:13] op_sel_hi:[0,1,1]
	v_fmac_f32_e32 v15, v54, v49
	v_pk_fma_f32 v[6:7], v[56:57], v[20:21], v[6:7] op_sel_hi:[0,1,1]
	v_pk_fma_f32 v[8:9], v[56:57], v[28:29], v[8:9] op_sel_hi:[0,1,1]
	v_pk_fma_f32 v[10:11], v[56:57], v[36:37], v[10:11] op_sel_hi:[0,1,1]
	v_pk_fma_f32 v[12:13], v[56:57], v[44:45], v[12:13] op_sel_hi:[0,1,1]
	v_fmac_f32_e32 v15, v56, v50
	v_pk_fma_f32 v[6:7], v[58:59], v[18:19], v[6:7] op_sel_hi:[0,1,1]
	v_pk_fma_f32 v[8:9], v[58:59], v[26:27], v[8:9] op_sel_hi:[0,1,1]
	v_pk_fma_f32 v[10:11], v[58:59], v[34:35], v[10:11] op_sel_hi:[0,1,1]
	v_pk_fma_f32 v[12:13], v[58:59], v[42:43], v[12:13] op_sel_hi:[0,1,1]
	v_fmac_f32_e32 v15, v58, v51
	s_waitcnt vmcnt(24)
	v_mov_b32_e32 v52, v116
	v_mov_b32_e32 v54, v117
	v_mov_b32_e32 v56, v118
	v_mov_b32_e32 v58, v119
	ds_read_b128 v[16:19], v3 offset:4096
	ds_read_b128 v[20:23], v3 offset:8192
	ds_read_b128 v[24:27], v3 offset:12288
	ds_read_b128 v[28:31], v3 offset:16384
	ds_read_b128 v[32:35], v3 offset:20480
	ds_read_b128 v[36:39], v3 offset:24576
	ds_read_b128 v[40:43], v3 offset:28672
	ds_read_b128 v[44:47], v3
	ds_read_b128 v[48:51], v3 offset:32768
	s_waitcnt lgkmcnt(8)
	v_mov_b32_e32 v61, v16
	s_waitcnt lgkmcnt(7)
	v_mov_b32_e32 v62, v20
	s_waitcnt lgkmcnt(6)
	v_mov_b32_e32 v63, v24
	s_waitcnt lgkmcnt(1)
	v_mov_b32_e32 v60, v44
	v_mov_b32_e32 v64, v28
	v_mov_b32_e32 v65, v32
	v_mov_b32_e32 v66, v36
	v_mov_b32_e32 v67, v40
	v_mov_b32_e32 v16, v45
	v_mov_b32_e32 v24, v21
	v_mov_b32_e32 v32, v29
	v_mov_b32_e32 v40, v37
	v_mov_b32_e32 v20, v46
	v_mov_b32_e32 v21, v18
	v_mov_b32_e32 v28, v22
	v_mov_b32_e32 v29, v26
	v_mov_b32_e32 v36, v30
	v_mov_b32_e32 v37, v34
	v_mov_b32_e32 v44, v38
	v_mov_b32_e32 v45, v42
	v_mov_b32_e32 v18, v47
	v_mov_b32_e32 v26, v23
	v_mov_b32_e32 v34, v31
	v_mov_b32_e32 v42, v39
	v_add_u32_e32 v3, 16, v3
	v_pk_fma_f32 v[6:7], v[52:53], v[60:61], v[6:7] op_sel_hi:[0,1,1]
	v_pk_fma_f32 v[8:9], v[52:53], v[62:63], v[8:9] op_sel_hi:[0,1,1]
	v_pk_fma_f32 v[10:11], v[52:53], v[64:65], v[10:11] op_sel_hi:[0,1,1]
	v_pk_fma_f32 v[12:13], v[52:53], v[66:67], v[12:13] op_sel_hi:[0,1,1]
	s_waitcnt lgkmcnt(0)
	v_fmac_f32_e32 v15, v52, v48
	v_pk_fma_f32 v[6:7], v[54:55], v[16:17], v[6:7] op_sel_hi:[0,1,1]
	v_pk_fma_f32 v[8:9], v[54:55], v[24:25], v[8:9] op_sel_hi:[0,1,1]
	v_pk_fma_f32 v[10:11], v[54:55], v[32:33], v[10:11] op_sel_hi:[0,1,1]
	v_pk_fma_f32 v[12:13], v[54:55], v[40:41], v[12:13] op_sel_hi:[0,1,1]
	v_fmac_f32_e32 v15, v54, v49
	v_pk_fma_f32 v[6:7], v[56:57], v[20:21], v[6:7] op_sel_hi:[0,1,1]
	v_pk_fma_f32 v[8:9], v[56:57], v[28:29], v[8:9] op_sel_hi:[0,1,1]
	v_pk_fma_f32 v[10:11], v[56:57], v[36:37], v[10:11] op_sel_hi:[0,1,1]
	v_pk_fma_f32 v[12:13], v[56:57], v[44:45], v[12:13] op_sel_hi:[0,1,1]
	v_fmac_f32_e32 v15, v56, v50
	v_pk_fma_f32 v[6:7], v[58:59], v[18:19], v[6:7] op_sel_hi:[0,1,1]
	v_pk_fma_f32 v[8:9], v[58:59], v[26:27], v[8:9] op_sel_hi:[0,1,1]
	v_pk_fma_f32 v[10:11], v[58:59], v[34:35], v[10:11] op_sel_hi:[0,1,1]
	v_pk_fma_f32 v[12:13], v[58:59], v[42:43], v[12:13] op_sel_hi:[0,1,1]
	v_fmac_f32_e32 v15, v58, v51
	s_waitcnt vmcnt(20)
	v_mov_b32_e32 v52, v120
	v_mov_b32_e32 v54, v121
	v_mov_b32_e32 v56, v122
	v_mov_b32_e32 v58, v123
	ds_read_b128 v[16:19], v3 offset:4096
	ds_read_b128 v[20:23], v3 offset:8192
	ds_read_b128 v[24:27], v3 offset:12288
	ds_read_b128 v[28:31], v3 offset:16384
	ds_read_b128 v[32:35], v3 offset:20480
	ds_read_b128 v[36:39], v3 offset:24576
	ds_read_b128 v[40:43], v3 offset:28672
	ds_read_b128 v[44:47], v3
	ds_read_b128 v[48:51], v3 offset:32768
	s_waitcnt lgkmcnt(8)
	v_mov_b32_e32 v61, v16
	s_waitcnt lgkmcnt(7)
	v_mov_b32_e32 v62, v20
	s_waitcnt lgkmcnt(6)
	v_mov_b32_e32 v63, v24
	s_waitcnt lgkmcnt(1)
	v_mov_b32_e32 v60, v44
	v_mov_b32_e32 v64, v28
	v_mov_b32_e32 v65, v32
	v_mov_b32_e32 v66, v36
	v_mov_b32_e32 v67, v40
	v_mov_b32_e32 v16, v45
	v_mov_b32_e32 v24, v21
	v_mov_b32_e32 v32, v29
	v_mov_b32_e32 v40, v37
	v_mov_b32_e32 v20, v46
	v_mov_b32_e32 v21, v18
	v_mov_b32_e32 v28, v22
	v_mov_b32_e32 v29, v26
	v_mov_b32_e32 v36, v30
	v_mov_b32_e32 v37, v34
	v_mov_b32_e32 v44, v38
	v_mov_b32_e32 v45, v42
	v_mov_b32_e32 v18, v47
	v_mov_b32_e32 v26, v23
	v_mov_b32_e32 v34, v31
	v_mov_b32_e32 v42, v39
	v_add_u32_e32 v3, 16, v3
	v_pk_fma_f32 v[6:7], v[52:53], v[60:61], v[6:7] op_sel_hi:[0,1,1]
	v_pk_fma_f32 v[8:9], v[52:53], v[62:63], v[8:9] op_sel_hi:[0,1,1]
	v_pk_fma_f32 v[10:11], v[52:53], v[64:65], v[10:11] op_sel_hi:[0,1,1]
	v_pk_fma_f32 v[12:13], v[52:53], v[66:67], v[12:13] op_sel_hi:[0,1,1]
	s_waitcnt lgkmcnt(0)
	v_fmac_f32_e32 v15, v52, v48
	v_pk_fma_f32 v[6:7], v[54:55], v[16:17], v[6:7] op_sel_hi:[0,1,1]
	v_pk_fma_f32 v[8:9], v[54:55], v[24:25], v[8:9] op_sel_hi:[0,1,1]
	v_pk_fma_f32 v[10:11], v[54:55], v[32:33], v[10:11] op_sel_hi:[0,1,1]
	v_pk_fma_f32 v[12:13], v[54:55], v[40:41], v[12:13] op_sel_hi:[0,1,1]
	v_fmac_f32_e32 v15, v54, v49
	v_pk_fma_f32 v[6:7], v[56:57], v[20:21], v[6:7] op_sel_hi:[0,1,1]
	v_pk_fma_f32 v[8:9], v[56:57], v[28:29], v[8:9] op_sel_hi:[0,1,1]
	v_pk_fma_f32 v[10:11], v[56:57], v[36:37], v[10:11] op_sel_hi:[0,1,1]
	v_pk_fma_f32 v[12:13], v[56:57], v[44:45], v[12:13] op_sel_hi:[0,1,1]
	v_fmac_f32_e32 v15, v56, v50
	v_pk_fma_f32 v[6:7], v[58:59], v[18:19], v[6:7] op_sel_hi:[0,1,1]
	v_pk_fma_f32 v[8:9], v[58:59], v[26:27], v[8:9] op_sel_hi:[0,1,1]
	v_pk_fma_f32 v[10:11], v[58:59], v[34:35], v[10:11] op_sel_hi:[0,1,1]
	v_pk_fma_f32 v[12:13], v[58:59], v[42:43], v[12:13] op_sel_hi:[0,1,1]
	v_fmac_f32_e32 v15, v58, v51
	s_waitcnt vmcnt(16)
	v_mov_b32_e32 v52, v124
	v_mov_b32_e32 v54, v125
	v_mov_b32_e32 v56, v126
	v_mov_b32_e32 v58, v127
	ds_read_b128 v[16:19], v3 offset:4096
	ds_read_b128 v[20:23], v3 offset:8192
	ds_read_b128 v[24:27], v3 offset:12288
	ds_read_b128 v[28:31], v3 offset:16384
	ds_read_b128 v[32:35], v3 offset:20480
	ds_read_b128 v[36:39], v3 offset:24576
	ds_read_b128 v[40:43], v3 offset:28672
	ds_read_b128 v[44:47], v3
	ds_read_b128 v[48:51], v3 offset:32768
	s_waitcnt lgkmcnt(8)
	v_mov_b32_e32 v61, v16
	s_waitcnt lgkmcnt(7)
	v_mov_b32_e32 v62, v20
	s_waitcnt lgkmcnt(6)
	v_mov_b32_e32 v63, v24
	s_waitcnt lgkmcnt(1)
	v_mov_b32_e32 v60, v44
	v_mov_b32_e32 v64, v28
	v_mov_b32_e32 v65, v32
	v_mov_b32_e32 v66, v36
	v_mov_b32_e32 v67, v40
	v_mov_b32_e32 v16, v45
	v_mov_b32_e32 v24, v21
	v_mov_b32_e32 v32, v29
	v_mov_b32_e32 v40, v37
	v_mov_b32_e32 v20, v46
	v_mov_b32_e32 v21, v18
	v_mov_b32_e32 v28, v22
	v_mov_b32_e32 v29, v26
	v_mov_b32_e32 v36, v30
	v_mov_b32_e32 v37, v34
	v_mov_b32_e32 v44, v38
	v_mov_b32_e32 v45, v42
	v_mov_b32_e32 v18, v47
	v_mov_b32_e32 v26, v23
	v_mov_b32_e32 v34, v31
	v_mov_b32_e32 v42, v39
	v_add_u32_e32 v3, 16, v3
	v_pk_fma_f32 v[6:7], v[52:53], v[60:61], v[6:7] op_sel_hi:[0,1,1]
	v_pk_fma_f32 v[8:9], v[52:53], v[62:63], v[8:9] op_sel_hi:[0,1,1]
	v_pk_fma_f32 v[10:11], v[52:53], v[64:65], v[10:11] op_sel_hi:[0,1,1]
	v_pk_fma_f32 v[12:13], v[52:53], v[66:67], v[12:13] op_sel_hi:[0,1,1]
	s_waitcnt lgkmcnt(0)
	v_fmac_f32_e32 v15, v52, v48
	v_pk_fma_f32 v[6:7], v[54:55], v[16:17], v[6:7] op_sel_hi:[0,1,1]
	v_pk_fma_f32 v[8:9], v[54:55], v[24:25], v[8:9] op_sel_hi:[0,1,1]
	v_pk_fma_f32 v[10:11], v[54:55], v[32:33], v[10:11] op_sel_hi:[0,1,1]
	v_pk_fma_f32 v[12:13], v[54:55], v[40:41], v[12:13] op_sel_hi:[0,1,1]
	v_fmac_f32_e32 v15, v54, v49
	v_pk_fma_f32 v[6:7], v[56:57], v[20:21], v[6:7] op_sel_hi:[0,1,1]
	v_pk_fma_f32 v[8:9], v[56:57], v[28:29], v[8:9] op_sel_hi:[0,1,1]
	v_pk_fma_f32 v[10:11], v[56:57], v[36:37], v[10:11] op_sel_hi:[0,1,1]
	v_pk_fma_f32 v[12:13], v[56:57], v[44:45], v[12:13] op_sel_hi:[0,1,1]
	v_fmac_f32_e32 v15, v56, v50
	v_pk_fma_f32 v[6:7], v[58:59], v[18:19], v[6:7] op_sel_hi:[0,1,1]
	v_pk_fma_f32 v[8:9], v[58:59], v[26:27], v[8:9] op_sel_hi:[0,1,1]
	v_pk_fma_f32 v[10:11], v[58:59], v[34:35], v[10:11] op_sel_hi:[0,1,1]
	v_pk_fma_f32 v[12:13], v[58:59], v[42:43], v[12:13] op_sel_hi:[0,1,1]
	v_fmac_f32_e32 v15, v58, v51
	s_waitcnt vmcnt(12)
	v_mov_b32_e32 v52, v128
	v_mov_b32_e32 v54, v129
	v_mov_b32_e32 v56, v130
	v_mov_b32_e32 v58, v131
	ds_read_b128 v[16:19], v3 offset:4096
	ds_read_b128 v[20:23], v3 offset:8192
	ds_read_b128 v[24:27], v3 offset:12288
	ds_read_b128 v[28:31], v3 offset:16384
	ds_read_b128 v[32:35], v3 offset:20480
	ds_read_b128 v[36:39], v3 offset:24576
	ds_read_b128 v[40:43], v3 offset:28672
	ds_read_b128 v[44:47], v3
	ds_read_b128 v[48:51], v3 offset:32768
	s_waitcnt lgkmcnt(8)
	v_mov_b32_e32 v61, v16
	s_waitcnt lgkmcnt(7)
	v_mov_b32_e32 v62, v20
	s_waitcnt lgkmcnt(6)
	v_mov_b32_e32 v63, v24
	s_waitcnt lgkmcnt(1)
	v_mov_b32_e32 v60, v44
	v_mov_b32_e32 v64, v28
	v_mov_b32_e32 v65, v32
	v_mov_b32_e32 v66, v36
	v_mov_b32_e32 v67, v40
	v_mov_b32_e32 v16, v45
	v_mov_b32_e32 v24, v21
	v_mov_b32_e32 v32, v29
	v_mov_b32_e32 v40, v37
	v_mov_b32_e32 v20, v46
	v_mov_b32_e32 v21, v18
	v_mov_b32_e32 v28, v22
	v_mov_b32_e32 v29, v26
	v_mov_b32_e32 v36, v30
	v_mov_b32_e32 v37, v34
	v_mov_b32_e32 v44, v38
	v_mov_b32_e32 v45, v42
	v_mov_b32_e32 v18, v47
	v_mov_b32_e32 v26, v23
	v_mov_b32_e32 v34, v31
	v_mov_b32_e32 v42, v39
	v_add_u32_e32 v3, 16, v3
	v_pk_fma_f32 v[6:7], v[52:53], v[60:61], v[6:7] op_sel_hi:[0,1,1]
	v_pk_fma_f32 v[8:9], v[52:53], v[62:63], v[8:9] op_sel_hi:[0,1,1]
	v_pk_fma_f32 v[10:11], v[52:53], v[64:65], v[10:11] op_sel_hi:[0,1,1]
	v_pk_fma_f32 v[12:13], v[52:53], v[66:67], v[12:13] op_sel_hi:[0,1,1]
	s_waitcnt lgkmcnt(0)
	v_fmac_f32_e32 v15, v52, v48
	v_pk_fma_f32 v[6:7], v[54:55], v[16:17], v[6:7] op_sel_hi:[0,1,1]
	v_pk_fma_f32 v[8:9], v[54:55], v[24:25], v[8:9] op_sel_hi:[0,1,1]
	v_pk_fma_f32 v[10:11], v[54:55], v[32:33], v[10:11] op_sel_hi:[0,1,1]
	v_pk_fma_f32 v[12:13], v[54:55], v[40:41], v[12:13] op_sel_hi:[0,1,1]
	v_fmac_f32_e32 v15, v54, v49
	v_pk_fma_f32 v[6:7], v[56:57], v[20:21], v[6:7] op_sel_hi:[0,1,1]
	v_pk_fma_f32 v[8:9], v[56:57], v[28:29], v[8:9] op_sel_hi:[0,1,1]
	v_pk_fma_f32 v[10:11], v[56:57], v[36:37], v[10:11] op_sel_hi:[0,1,1]
	v_pk_fma_f32 v[12:13], v[56:57], v[44:45], v[12:13] op_sel_hi:[0,1,1]
	v_fmac_f32_e32 v15, v56, v50
	v_pk_fma_f32 v[6:7], v[58:59], v[18:19], v[6:7] op_sel_hi:[0,1,1]
	v_pk_fma_f32 v[8:9], v[58:59], v[26:27], v[8:9] op_sel_hi:[0,1,1]
	v_pk_fma_f32 v[10:11], v[58:59], v[34:35], v[10:11] op_sel_hi:[0,1,1]
	v_pk_fma_f32 v[12:13], v[58:59], v[42:43], v[12:13] op_sel_hi:[0,1,1]
	v_fmac_f32_e32 v15, v58, v51
	s_waitcnt vmcnt(8)
	v_mov_b32_e32 v52, v132
	v_mov_b32_e32 v54, v133
	v_mov_b32_e32 v56, v134
	v_mov_b32_e32 v58, v135
	ds_read_b128 v[16:19], v3 offset:4096
	ds_read_b128 v[20:23], v3 offset:8192
	ds_read_b128 v[24:27], v3 offset:12288
	ds_read_b128 v[28:31], v3 offset:16384
	ds_read_b128 v[32:35], v3 offset:20480
	ds_read_b128 v[36:39], v3 offset:24576
	ds_read_b128 v[40:43], v3 offset:28672
	ds_read_b128 v[44:47], v3
	ds_read_b128 v[48:51], v3 offset:32768
	s_waitcnt lgkmcnt(8)
	v_mov_b32_e32 v61, v16
	s_waitcnt lgkmcnt(7)
	v_mov_b32_e32 v62, v20
	s_waitcnt lgkmcnt(6)
	v_mov_b32_e32 v63, v24
	s_waitcnt lgkmcnt(1)
	v_mov_b32_e32 v60, v44
	v_mov_b32_e32 v64, v28
	v_mov_b32_e32 v65, v32
	v_mov_b32_e32 v66, v36
	v_mov_b32_e32 v67, v40
	v_mov_b32_e32 v16, v45
	v_mov_b32_e32 v24, v21
	v_mov_b32_e32 v32, v29
	v_mov_b32_e32 v40, v37
	v_mov_b32_e32 v20, v46
	v_mov_b32_e32 v21, v18
	v_mov_b32_e32 v28, v22
	v_mov_b32_e32 v29, v26
	v_mov_b32_e32 v36, v30
	v_mov_b32_e32 v37, v34
	v_mov_b32_e32 v44, v38
	v_mov_b32_e32 v45, v42
	v_mov_b32_e32 v18, v47
	v_mov_b32_e32 v26, v23
	v_mov_b32_e32 v34, v31
	v_mov_b32_e32 v42, v39
	v_add_u32_e32 v3, 16, v3
	v_pk_fma_f32 v[6:7], v[52:53], v[60:61], v[6:7] op_sel_hi:[0,1,1]
	v_pk_fma_f32 v[8:9], v[52:53], v[62:63], v[8:9] op_sel_hi:[0,1,1]
	v_pk_fma_f32 v[10:11], v[52:53], v[64:65], v[10:11] op_sel_hi:[0,1,1]
	v_pk_fma_f32 v[12:13], v[52:53], v[66:67], v[12:13] op_sel_hi:[0,1,1]
	s_waitcnt lgkmcnt(0)
	v_fmac_f32_e32 v15, v52, v48
	v_pk_fma_f32 v[6:7], v[54:55], v[16:17], v[6:7] op_sel_hi:[0,1,1]
	v_pk_fma_f32 v[8:9], v[54:55], v[24:25], v[8:9] op_sel_hi:[0,1,1]
	v_pk_fma_f32 v[10:11], v[54:55], v[32:33], v[10:11] op_sel_hi:[0,1,1]
	v_pk_fma_f32 v[12:13], v[54:55], v[40:41], v[12:13] op_sel_hi:[0,1,1]
	v_fmac_f32_e32 v15, v54, v49
	v_pk_fma_f32 v[6:7], v[56:57], v[20:21], v[6:7] op_sel_hi:[0,1,1]
	v_pk_fma_f32 v[8:9], v[56:57], v[28:29], v[8:9] op_sel_hi:[0,1,1]
	v_pk_fma_f32 v[10:11], v[56:57], v[36:37], v[10:11] op_sel_hi:[0,1,1]
	v_pk_fma_f32 v[12:13], v[56:57], v[44:45], v[12:13] op_sel_hi:[0,1,1]
	v_fmac_f32_e32 v15, v56, v50
	v_pk_fma_f32 v[6:7], v[58:59], v[18:19], v[6:7] op_sel_hi:[0,1,1]
	v_pk_fma_f32 v[8:9], v[58:59], v[26:27], v[8:9] op_sel_hi:[0,1,1]
	v_pk_fma_f32 v[10:11], v[58:59], v[34:35], v[10:11] op_sel_hi:[0,1,1]
	v_pk_fma_f32 v[12:13], v[58:59], v[42:43], v[12:13] op_sel_hi:[0,1,1]
	v_fmac_f32_e32 v15, v58, v51
	s_waitcnt vmcnt(4)
	v_mov_b32_e32 v52, v136
	v_mov_b32_e32 v54, v137
	v_mov_b32_e32 v56, v138
	v_mov_b32_e32 v58, v139
	ds_read_b128 v[16:19], v3 offset:4096
	ds_read_b128 v[20:23], v3 offset:8192
	ds_read_b128 v[24:27], v3 offset:12288
	ds_read_b128 v[28:31], v3 offset:16384
	ds_read_b128 v[32:35], v3 offset:20480
	ds_read_b128 v[36:39], v3 offset:24576
	ds_read_b128 v[40:43], v3 offset:28672
	ds_read_b128 v[44:47], v3
	ds_read_b128 v[48:51], v3 offset:32768
	s_waitcnt lgkmcnt(8)
	v_mov_b32_e32 v61, v16
	s_waitcnt lgkmcnt(7)
	v_mov_b32_e32 v62, v20
	s_waitcnt lgkmcnt(6)
	v_mov_b32_e32 v63, v24
	s_waitcnt lgkmcnt(1)
	v_mov_b32_e32 v60, v44
	v_mov_b32_e32 v64, v28
	v_mov_b32_e32 v65, v32
	v_mov_b32_e32 v66, v36
	v_mov_b32_e32 v67, v40
	v_mov_b32_e32 v16, v45
	v_mov_b32_e32 v24, v21
	v_mov_b32_e32 v32, v29
	v_mov_b32_e32 v40, v37
	v_mov_b32_e32 v20, v46
	v_mov_b32_e32 v21, v18
	v_mov_b32_e32 v28, v22
	v_mov_b32_e32 v29, v26
	v_mov_b32_e32 v36, v30
	v_mov_b32_e32 v37, v34
	v_mov_b32_e32 v44, v38
	v_mov_b32_e32 v45, v42
	v_mov_b32_e32 v18, v47
	v_mov_b32_e32 v26, v23
	v_mov_b32_e32 v34, v31
	v_mov_b32_e32 v42, v39
	v_add_u32_e32 v3, 16, v3
	v_pk_fma_f32 v[6:7], v[52:53], v[60:61], v[6:7] op_sel_hi:[0,1,1]
	v_pk_fma_f32 v[8:9], v[52:53], v[62:63], v[8:9] op_sel_hi:[0,1,1]
	v_pk_fma_f32 v[10:11], v[52:53], v[64:65], v[10:11] op_sel_hi:[0,1,1]
	v_pk_fma_f32 v[12:13], v[52:53], v[66:67], v[12:13] op_sel_hi:[0,1,1]
	s_waitcnt lgkmcnt(0)
	v_fmac_f32_e32 v15, v52, v48
	v_pk_fma_f32 v[6:7], v[54:55], v[16:17], v[6:7] op_sel_hi:[0,1,1]
	v_pk_fma_f32 v[8:9], v[54:55], v[24:25], v[8:9] op_sel_hi:[0,1,1]
	v_pk_fma_f32 v[10:11], v[54:55], v[32:33], v[10:11] op_sel_hi:[0,1,1]
	v_pk_fma_f32 v[12:13], v[54:55], v[40:41], v[12:13] op_sel_hi:[0,1,1]
	v_fmac_f32_e32 v15, v54, v49
	v_pk_fma_f32 v[6:7], v[56:57], v[20:21], v[6:7] op_sel_hi:[0,1,1]
	v_pk_fma_f32 v[8:9], v[56:57], v[28:29], v[8:9] op_sel_hi:[0,1,1]
	v_pk_fma_f32 v[10:11], v[56:57], v[36:37], v[10:11] op_sel_hi:[0,1,1]
	v_pk_fma_f32 v[12:13], v[56:57], v[44:45], v[12:13] op_sel_hi:[0,1,1]
	v_fmac_f32_e32 v15, v56, v50
	v_pk_fma_f32 v[6:7], v[58:59], v[18:19], v[6:7] op_sel_hi:[0,1,1]
	v_pk_fma_f32 v[8:9], v[58:59], v[26:27], v[8:9] op_sel_hi:[0,1,1]
	v_pk_fma_f32 v[10:11], v[58:59], v[34:35], v[10:11] op_sel_hi:[0,1,1]
	v_pk_fma_f32 v[12:13], v[58:59], v[42:43], v[12:13] op_sel_hi:[0,1,1]
	v_fmac_f32_e32 v15, v58, v51
	s_waitcnt vmcnt(0)
	v_mov_b32_e32 v52, v140
	v_mov_b32_e32 v54, v141
	v_mov_b32_e32 v56, v142
	v_mov_b32_e32 v58, v143
	ds_read_b128 v[16:19], v3 offset:4096
	ds_read_b128 v[20:23], v3 offset:8192
	ds_read_b128 v[24:27], v3 offset:12288
	ds_read_b128 v[28:31], v3 offset:16384
	ds_read_b128 v[32:35], v3 offset:20480
	ds_read_b128 v[36:39], v3 offset:24576
	ds_read_b128 v[40:43], v3 offset:28672
	ds_read_b128 v[44:47], v3
	ds_read_b128 v[48:51], v3 offset:32768
	s_waitcnt lgkmcnt(8)
	v_mov_b32_e32 v61, v16
	s_waitcnt lgkmcnt(7)
	v_mov_b32_e32 v62, v20
	s_waitcnt lgkmcnt(6)
	v_mov_b32_e32 v63, v24
	s_waitcnt lgkmcnt(1)
	v_mov_b32_e32 v60, v44
	v_mov_b32_e32 v64, v28
	v_mov_b32_e32 v65, v32
	v_mov_b32_e32 v66, v36
	v_mov_b32_e32 v67, v40
	v_mov_b32_e32 v16, v45
	v_mov_b32_e32 v24, v21
	v_mov_b32_e32 v32, v29
	v_mov_b32_e32 v40, v37
	v_mov_b32_e32 v20, v46
	v_mov_b32_e32 v21, v18
	v_mov_b32_e32 v28, v22
	v_mov_b32_e32 v29, v26
	v_mov_b32_e32 v36, v30
	v_mov_b32_e32 v37, v34
	v_mov_b32_e32 v44, v38
	v_mov_b32_e32 v45, v42
	v_mov_b32_e32 v18, v47
	v_mov_b32_e32 v26, v23
	v_mov_b32_e32 v34, v31
	v_mov_b32_e32 v42, v39
	v_add_u32_e32 v3, 16, v3
	v_pk_fma_f32 v[6:7], v[52:53], v[60:61], v[6:7] op_sel_hi:[0,1,1]
	v_pk_fma_f32 v[8:9], v[52:53], v[62:63], v[8:9] op_sel_hi:[0,1,1]
	v_pk_fma_f32 v[10:11], v[52:53], v[64:65], v[10:11] op_sel_hi:[0,1,1]
	v_pk_fma_f32 v[12:13], v[52:53], v[66:67], v[12:13] op_sel_hi:[0,1,1]
	s_waitcnt lgkmcnt(0)
	v_fmac_f32_e32 v15, v52, v48
	v_pk_fma_f32 v[6:7], v[54:55], v[16:17], v[6:7] op_sel_hi:[0,1,1]
	v_pk_fma_f32 v[8:9], v[54:55], v[24:25], v[8:9] op_sel_hi:[0,1,1]
	v_pk_fma_f32 v[10:11], v[54:55], v[32:33], v[10:11] op_sel_hi:[0,1,1]
	v_pk_fma_f32 v[12:13], v[54:55], v[40:41], v[12:13] op_sel_hi:[0,1,1]
	v_fmac_f32_e32 v15, v54, v49
	v_pk_fma_f32 v[6:7], v[56:57], v[20:21], v[6:7] op_sel_hi:[0,1,1]
	v_pk_fma_f32 v[8:9], v[56:57], v[28:29], v[8:9] op_sel_hi:[0,1,1]
	v_pk_fma_f32 v[10:11], v[56:57], v[36:37], v[10:11] op_sel_hi:[0,1,1]
	v_pk_fma_f32 v[12:13], v[56:57], v[44:45], v[12:13] op_sel_hi:[0,1,1]
	v_fmac_f32_e32 v15, v56, v50
	v_pk_fma_f32 v[6:7], v[58:59], v[18:19], v[6:7] op_sel_hi:[0,1,1]
	v_pk_fma_f32 v[8:9], v[58:59], v[26:27], v[8:9] op_sel_hi:[0,1,1]
	v_pk_fma_f32 v[10:11], v[58:59], v[34:35], v[10:11] op_sel_hi:[0,1,1]
	v_pk_fma_f32 v[12:13], v[58:59], v[42:43], v[12:13] op_sel_hi:[0,1,1]
	v_fmac_f32_e32 v15, v58, v51
	v_lshl_add_u32 v4, v2, 2, 0
	s_movk_i32 s14, 0x900
	v_mad_u64_u32 v[16:17], s[14:15], v0, s14, v[4:5]
	s_movk_i32 s14, 0x240
	s_nop 0
	v_cmp_gt_i32_e32 vcc, s14, v14
	ds_write2st64_b32 v16, v6, v7 offset0:144 offset1:145
	ds_write2st64_b32 v16, v8, v9 offset0:146 offset1:147
	ds_write2st64_b32 v16, v10, v11 offset0:148 offset1:149
	ds_write2st64_b32 v16, v12, v13 offset0:150 offset1:151
	ds_write_b32 v16, v15 offset:38912
	s_waitcnt lgkmcnt(0)
	s_barrier
	s_and_saveexec_b64 s[14:15], vcc
	s_cbranch_execz .LBB0_1796
	s_add_u32 s16, s72, s12
	s_addc_u32 s17, s73, s13
	s_and_b64 s[12:13], s[10:11], exec
	s_cselect_b32 s12, 0x1800, 0
	s_add_i32 s13, s28, s12
	v_or_b32_e32 v0, s13, v2
	s_and_b64 s[10:11], s[10:11], exec
	v_lshl_add_u64 v[6:7], v[0:1], 2, s[90:91]
	v_lshlrev_b32_e32 v0, 2, v2
	s_cselect_b32 s12, 9, 0
	v_lshl_add_u64 v[2:3], s[16:17], 0, v[0:1]
	s_mov_b64 s[10:11], 0
